# SSD: B and state tiles re-pitched to 288 bytes (bank-conflict-free row-fragment reads), state tile moved to the freed C region
# speedup vs baseline: 1.0363x; 1.0046x over previous
; #define LAS __attribute__((address_space(3)))
; __device__ __forceinline__ void phase_C1(const Args& a, unsigned char* ws, const int bid, int l, LAS unsigned char* lds, int tid, int wave, int lane) {
;     bf16_t* z = (bf16_t*)(ws + WS_Z);
;     const bf16_t* xbc = (const bf16_t*)(ws + WS_XBC);
;     const float* DT = (const float*)(ws + WS_DT);
;     LAS unsigned char* L_C = lds; LAS unsigned char* L_B = lds + 34816; LAS unsigned char* L_M = lds + 69632; LAS unsigned char* L_X = lds + 104448; LAS unsigned char* L_H = lds + 122880;
;     LAS float* cs = (LAS float*)(lds + 140288); LAS float* dtv = cs + 128; LAS float* wgt = cs + 256; LAS float* ecs = cs + 384; LAS float* f2dt = cs + 512; LAS float* refarr = cs + 640; LAS float* totp = cs + 656;
;     const int fr = lane & 15, fq = lane >> 4, wr = wave >> 1, wc = wave & 1;
;     const int qt = wave < 4 ? wave : 11 - wave;
;     const int rb = fr * 272 + fq * 16;
;     const int trB = (8 * fq + (fr >> 2)) * 272 + 8 * (lane & 3);
;     const int trX = (8 * fq + (fr >> 2)) * 144 + 8 * (lane & 3);
;     const int trXp = (8 * fq + (fr >> 2)) * 144 + 16 * (lane & 3);
;     const int rbH = (8 * (fr >> 2) + (fr & 3)) * 272 + fq * 16;
;     const unsigned offCB = (unsigned)(tid >> 4) * 4096u + (unsigned)(tid & 15) * 8u, offX = (unsigned)(tid >> 3) * 4096u + (unsigned)(tid & 7) * 8u;
;     const int wCB = (tid >> 4) * 272 + (tid & 15) * 16, wX = (tid >> 3) * 144 + (tid & 7) * 16;
.LBB0_84:
	s_cmp_eq_u32 s60, 3
	s_mov_b64 s[0:1], -1
	s_cbranch_scc0 .LBB0_127
	v_writelane_b32 v254, s61, 54
	v_writelane_b32 v254, s62, 55
	s_cmpk_gt_i32 s68, 0xff
	s_mov_b32 s3, s33
	v_writelane_b32 v254, s63, 56
	v_writelane_b32 v254, s60, 57
	v_writelane_b32 v254, s82, 58
	s_nop 1
	v_writelane_b32 v254, s83, 59
	s_nop 0
	v_readlane_b32 s60, v254, 39
	v_readlane_b32 s61, v254, 40
	s_cbranch_scc1 .LBB0_128
	v_readlane_b32 s0, v254, 47
	v_readlane_b32 s1, v254, 48
	s_add_u32 s2, s0, 0x19afe000
	v_writelane_b32 v254, s2, 60
	s_addc_u32 s2, s1, 0
	s_add_u32 s68, s0, 0x4c37e000
	s_addc_u32 s93, s1, 0
	s_add_u32 s0, s0, 0x2be000
	v_writelane_b32 v254, s2, 61
	s_addc_u32 s1, s1, 0
	v_writelane_b32 v254, s0, 62
	v_and_b32_e32 v0, 7, v164
	v_ashrrev_i32_e32 v2, 3, v164
	v_writelane_b32 v254, s1, 63
	s_movk_i32 s2, 0x90
	v_readlane_b32 s5, v254, 49
	s_sub_i32 s0, 11, s5
	s_cmp_lt_i32 s5, 4
	v_readlane_b32 s6, v254, 58
	s_cselect_b32 s0, s5, s0
	s_lshl_b32 s3, s6, 6
	v_and_b32_e32 v6, 15, v164
	v_lshlrev_b32_e32 v7, 3, v0
	v_readlane_b32 s8, v254, 54
	v_writelane_b32 v255, s3, 0
	s_lshl_b32 s3, s6, 5
	v_mul_lo_u32 v3, v2, s2
	v_ashrrev_i32_e32 v4, 4, v164
	s_movk_i32 s10, 0x110
	v_lshl_or_b32 v104, v2, 12, v7
	v_lshlrev_b32_e32 v2, 3, v6
	s_ashr_i32 s1, s8, 7
	v_readlane_b32 s7, v254, 59
	v_writelane_b32 v255, s3, 1
	s_movk_i32 s3, 0x1100
	v_mul_lo_u32 v5, v4, s10
	v_lshl_or_b32 v106, v4, 12, v2
	v_bfe_u32 v2, v164, 2, 2
	v_and_b32_e32 v4, 3, v164
	v_lshrrev_b32_e32 v10, 4, v206
	v_cmp_gt_i32_e64 s[6:7], s3, v164
	s_cmp_lt_u32 s8, 64
	v_lshlrev_b32_e32 v15, 3, v206
	v_readlane_b32 s12, v253, 45
	v_readlane_b32 s13, v253, 46
	v_readlane_b32 s4, v253, 47
	v_readlane_b32 s14, v253, 48
	v_readlane_b32 s38, v253, 49
	v_readlane_b32 s42, v253, 50
	v_lshl_or_b32 v7, v2, 3, v4
	v_lshlrev_b32_e32 v108, 3, v10
	v_writelane_b32 v255, s6, 2
	s_cselect_b64 s[24:25], -1, 0
	s_cmp_gt_u32 s8, 63
	v_readlane_b32 s3, v253, 43
	v_add_u32_e32 v120, s12, v15
	v_add_u32_e32 v121, s13, v15
	v_add_u32_e32 v122, s4, v15
	v_add_u32_e32 v123, s14, v15
	v_add_u32_e32 v124, s38, v15
	v_mov_b32_e32 v15, s42
	v_or_b32_e32 v2, v108, v2
	v_writelane_b32 v255, s7, 3
	s_cselect_b64 s[6:7], -1, 0
	v_mad_u32_u24 v7, v7, s10, v15
	v_mov_b32_e32 v15, s3
	v_lshl_add_u32 v125, v10, 5, s4
	s_lshl_b32 s4, s5, 7
	s_lshl_b32 s5, s0, 4
	v_lshlrev_b32_e32 v9, 4, v4
	v_lshlrev_b32_e32 v4, 3, v4
	v_mul_u32_u24_e32 v11, 0x110, v2
	v_mad_u32_u24 v2, v2, s2, v15
	v_or_b32_e32 v126, s5, v6
	v_and_b32_e32 v8, 48, v164
	v_add_u32_e32 v15, v2, v4
	v_add3_u32 v4, 0, v11, v4
	v_lshlrev_b32_e32 v11, 2, v126
	v_add_u32_e32 v3, s3, v3
	v_readlane_b32 s11, v253, 44
	v_add_u32_e32 v13, s3, v8
	s_lshl_b32 s3, s1, 5
	s_and_b32 s4, s4, 0x80
	v_add_u32_e32 v127, s12, v11
	v_add_u32_e32 v128, s14, v11
	v_lshlrev_b32_e32 v10, 2, v10
	v_mul_lo_u32 v11, v126, s10
	v_mad_u32_u24 v12, v6, s10, v8
	v_add_u32_e32 v129, s11, v11
	v_or_b32_e32 v11, s5, v10
	v_lshl_or_b32 v18, s1, 4, v6
	s_cmp_eq_u32 s0, 1
	v_add_u32_e32 v118, 0, v12
	v_add_u32_e32 v12, s11, v12
	v_lshlrev_b32_e32 v16, 2, v11
	v_mul_lo_u32 v18, v18, s10
	s_cselect_b64 s[10:11], -1, 0
	s_cmp_eq_u32 s0, 2
	v_add_u32_e32 v130, s12, v16
	v_add_u32_e32 v131, s13, v16
	s_cselect_b64 s[12:13], -1, 0
	s_cmp_eq_u32 s0, 3
	s_cselect_b64 s[14:15], -1, 0
	s_cmp_eq_u32 s0, 4
	s_cselect_b64 s[16:17], -1, 0
	s_cmp_eq_u32 s0, 5
	s_cselect_b64 s[18:19], -1, 0
	s_cmp_eq_u32 s0, 6
	s_cselect_b64 s[20:21], -1, 0
	s_cmp_eq_u32 s0, 7
	v_writelane_b32 v255, s6, 4
	s_cselect_b64 s[22:23], -1, 0
	s_cmp_gt_i32 s0, 0
	v_writelane_b32 v255, s7, 5
	s_cselect_b64 s[44:45], -1, 0
	v_writelane_b32 v255, s44, 6
	s_cmp_lt_i32 s0, 0
	s_mul_i32 s33, s0, 0x1100
	v_writelane_b32 v255, s45, 7
	s_cselect_b64 s[44:45], -1, 0
	v_writelane_b32 v255, s44, 8
	s_cmp_gt_i32 s0, 1
	v_or_b32_e32 v26, 1, v11
	v_writelane_b32 v255, s45, 9
	s_cselect_b64 s[44:45], -1, 0
	v_writelane_b32 v255, s44, 10
	s_cmp_lt_i32 s0, 1
	v_lshl_add_u32 v5, v6, 4, v5
	v_writelane_b32 v255, s45, 11
	s_cselect_b64 s[44:45], -1, 0
	v_writelane_b32 v255, s44, 12
	s_cmp_gt_i32 s0, 2
	v_and_b32_e32 v19, 48, v206
	v_writelane_b32 v255, s45, 13
	s_cselect_b64 s[44:45], -1, 0
	v_writelane_b32 v255, s44, 14
	s_cmp_lt_i32 s0, 2
	v_add_u32_e32 v132, s38, v19
	v_writelane_b32 v255, s45, 15
	s_cselect_b64 s[44:45], -1, 0
	v_writelane_b32 v255, s44, 16
	s_cmp_gt_i32 s0, 3
	v_or_b32_e32 v19, 16, v10
	v_writelane_b32 v255, s45, 17
	s_cselect_b64 s[44:45], -1, 0
; __device__ __forceinline__ void phase_C1(const Args& a, unsigned char* ws, const int bid, int l, LAS unsigned char* lds, int tid, int wave, int lane) {
;     ...
;     const int qt = wave < 4 ? wave : 11 - wave;
;     const int rb = fr * 272 + fq * 16;
;     const int trB = (8 * fq + (fr >> 2)) * 272 + 8 * (lane & 3);
;     const int trX = (8 * fq + (fr >> 2)) * 144 + 8 * (lane & 3);
;     const int trXp = (8 * fq + (fr >> 2)) * 144 + 16 * (lane & 3);
;     const int rbH = (8 * (fr >> 2) + (fr & 3)) * 272 + fq * 16;
;     const unsigned offCB = (unsigned)(tid >> 4) * 4096u + (unsigned)(tid & 15) * 8u, offX = (unsigned)(tid >> 3) * 4096u + (unsigned)(tid & 7) * 8u;
;     const int wCB = (tid >> 4) * 272 + (tid & 15) * 16, wX = (tid >> 3) * 144 + (tid & 7) * 16;
	v_writelane_b32 v255, s44, 18
	s_cmp_lt_i32 s0, 3
	v_or_b32_e32 v20, 32, v10
	v_writelane_b32 v255, s45, 19
	s_cselect_b64 s[44:45], -1, 0
	v_writelane_b32 v255, s44, 20
	s_cmp_gt_i32 s0, 4
	v_or_b32_e32 v21, 48, v10
	v_writelane_b32 v255, s45, 21
	s_cselect_b64 s[44:45], -1, 0
	v_writelane_b32 v255, s44, 22
	s_cmp_lt_i32 s0, 4
	v_or_b32_e32 v22, 64, v10
	v_writelane_b32 v255, s45, 23
	s_cselect_b64 s[44:45], -1, 0
	v_writelane_b32 v255, s44, 24
	s_cmp_gt_i32 s0, 5
	v_or_b32_e32 v23, 0x50, v10
	v_writelane_b32 v255, s45, 25
	s_cselect_b64 s[44:45], -1, 0
	v_writelane_b32 v255, s44, 26
	s_cmp_lt_i32 s0, 5
	v_or_b32_e32 v24, 0x60, v10
	v_writelane_b32 v255, s45, 27
	s_cselect_b64 s[44:45], -1, 0
	v_writelane_b32 v255, s44, 28
	s_cmp_gt_i32 s0, 6
	v_or_b32_e32 v25, 0x70, v10
	v_writelane_b32 v255, s45, 29
	s_cselect_b64 s[44:45], -1, 0
	v_writelane_b32 v255, s44, 30
	s_cmp_lt_i32 s0, 6
	v_add_u32_e32 v141, s4, v4
	v_writelane_b32 v255, s45, 31
	s_cselect_b64 s[44:45], -1, 0
	v_writelane_b32 v255, s44, 32
	s_cmp_gt_i32 s0, 7
	v_or_b32_e32 v4, 3, v11
	v_writelane_b32 v255, s45, 33
	s_cselect_b64 s[44:45], -1, 0
	v_writelane_b32 v255, s44, 34
	s_cmp_lt_i32 s0, 7
	s_cselect_b64 s[0:1], -1, 0
	v_writelane_b32 v255, s45, 35
	v_writelane_b32 v255, s0, 36
	v_mul_lo_u32 v17, v126, s2
	v_add_u32_e32 v140, s3, v15
	v_writelane_b32 v255, s1, 37
	v_cmp_le_u32_e64 s[0:1], v10, v6
	v_cmp_le_i32_e64 s[2:3], v4, v126
	v_lshlrev_b32_e32 v1, 4, v0
	v_writelane_b32 v255, s0, 38
	v_cmp_eq_u32_e64 s[6:7], 0, v0
	v_lshrrev_b32_e32 v0, 1, v206
	v_writelane_b32 v255, s1, 39
	v_cmp_ge_u32_e64 s[0:1], v10, v6
	v_and_b32_e32 v14, 56, v164
	v_add_u32_e32 v0, 0, v0
	v_writelane_b32 v255, s0, 40
	v_lshlrev_b32_e32 v16, 1, v11
	v_lshl_add_u32 v133, v19, 2, s38
	v_writelane_b32 v255, s1, 41
	v_cmp_lt_u32_e64 s[0:1], v10, v6
	v_or_b32_e32 v6, 2, v11
	v_lshlrev_b32_e32 v19, 1, v19
	v_writelane_b32 v255, s0, 42
	v_lshl_add_u32 v134, v20, 2, s38
	v_lshlrev_b32_e32 v20, 1, v20
	v_writelane_b32 v255, s1, 43
	v_cmp_ge_i32_e64 s[0:1], v26, v126
	v_lshl_add_u32 v135, v21, 2, s38
	v_lshlrev_b32_e32 v21, 1, v21
	v_writelane_b32 v255, s0, 44
	v_lshl_add_u32 v136, v22, 2, s38
	v_lshlrev_b32_e32 v22, 1, v22
	v_writelane_b32 v255, s1, 45
	s_add_i32 s0, s4, s42
	v_add_u32_e32 v10, s0, v18
	v_cmp_le_i32_e64 s[0:1], v6, v126
	v_lshl_add_u32 v137, v23, 2, s38
	v_lshlrev_b32_e32 v23, 1, v23
	v_writelane_b32 v255, s0, 46
	v_lshl_add_u32 v138, v24, 2, s38
	v_lshlrev_b32_e32 v24, 1, v24
	v_writelane_b32 v255, s1, 47
	v_cmp_ge_i32_e64 s[0:1], v6, v126
	v_lshl_add_u32 v139, v25, 2, s38
	v_lshlrev_b32_e32 v25, 1, v25
	v_writelane_b32 v255, s0, 48
	v_add_u32_e32 v146, 0x22e00, v0
	v_and_or_b32 v0, v201, 64, v14
	v_writelane_b32 v255, s1, 49
	v_writelane_b32 v255, s2, 50
	v_readlane_b32 s0, v254, 53
	v_mov_b32_e32 v107, v161
	v_writelane_b32 v255, s3, 51
	v_cmp_ge_i32_e64 s[2:3], v4, v126
	v_mov_b32_e32 v105, v161
	v_lshlrev_b32_e32 v109, 1, v206
	v_writelane_b32 v255, s2, 52
	v_or_b32_e32 v119, 7, v206
	v_cmp_eq_u32_e64 s[8:9], 0, v206
	v_add_u32_e32 v142, 0xfffffe00, v164
	v_lshl_add_u32 v143, v164, 2, s42
	v_lshlrev_b32_e32 v160, 1, v108
	v_add_u32_e32 v144, 0, v5
	v_add_u32_e32 v145, v3, v1
	v_add_u32_e32 v147, v7, v8
	v_add_u32_e32 v148, v129, v19
	v_add_u32_e32 v149, v129, v20
	s_waitcnt lgkmcnt(0)
	v_add_u32_e32 v150, v129, v21
	v_add_u32_e32 v151, v129, v22
	v_add_u32_e32 v152, v129, v23
	v_add_u32_e32 v153, v129, v24
	v_add_u32_e32 v154, v129, v25
	v_add_u32_e32 v155, v129, v16
	v_add_u32_e32 v156, s33, v12
	v_add_u32_e32 v157, v2, v9
	v_add_u32_e32 v158, v10, v108
	v_lshlrev_b32_e32 v159, 2, v0
	v_add_u32_e32 v165, v13, v17
	v_add_u32_e32 v147, 0x1e000, v118
	v_and_b32_e32 v0, 3, v164
	v_lshlrev_b32_e32 v0, 3, v0
	v_sub_u32_e32 v157, v157, v0
	v_and_b32_e32 v0, 15, v164
	v_bfe_u32 v1, v164, 4, 2
	v_mul_u32_u24_e32 v2, 0x120, v0
	v_lshl_add_u32 v118, v1, 4, v2
	v_mov_b32_e32 v147, v118
	v_lshrrev_b32_e32 v2, 4, v164
	v_mul_u32_u24_e32 v2, 0x120, v2
	v_lshl_add_u32 v144, v0, 4, v2
	v_lshrrev_b32_e32 v2, 2, v0
	v_lshl_add_u32 v2, v1, 3, v2
	v_mul_u32_u24_e32 v2, 0x120, v2
	v_and_b32_e32 v3, 3, v164
	v_lshl_add_u32 v2, v3, 3, v2
	v_bfe_u32 v3, v164, 6, 1
	v_lshl_add_u32 v141, v3, 7, v2
	v_lshrrev_b32_e32 v2, 7, v164
	v_lshl_add_u32 v2, v2, 4, v0
	v_mul_u32_u24_e32 v2, 0x120, v2
	v_lshl_add_u32 v2, v3, 7, v2
	v_lshl_add_u32 v158, v1, 3, v2
	v_lshlrev_b32_e32 v143, 2, v164
	s_mov_b32 s1, s0
	v_writelane_b32 v255, s3, 53
	s_branch .LBB0_88

; #define LAS __attribute__((address_space(3)))
; __device__ __forceinline__ void phase_C1(const Args& a, unsigned char* ws, const int bid, int l, LAS unsigned char* lds, int tid, int wave, int lane) {
;     ...
;         for (int i = tid; i < 17408 / 4; i += 512) ((LAS unsigned*)L_H)[i] = 0u;
.LBB0_90:
	v_add_u32_e32 v1, 0x200, v1
	s_movk_i32 s38, 0xfff
	v_cmp_lt_i32_e32 vcc, s38, v1
	ds_write_b32 v0, v161
	s_or_b64 s[42:43], vcc, s[42:43]
	v_add_u32_e32 v0, 0x800, v0
	s_andn2_b64 exec, exec, s[42:43]
	s_cbranch_execnz .LBB0_90

; #define LAS __attribute__((address_space(3)))
; #define INP(k) inp_(a.in[k])
; __device__ __forceinline__ void phase_C1(const Args& a, unsigned char* ws, const int bid, int l, LAS unsigned char* lds, int tid, int wave, int lane) {
;     ...
;     for (int item = bid; item < 256; item += gridDim.x) {
;         const int combo = (item & 7) * 8 + (item >> 5), hq = (item >> 3) & 3;
;         const int b = combo >> 4, g = (combo >> 1) & 7, dir = combo & 1, h = 4 * g + hq;
;         const float Acoef = -__expf(INP(12)[l * 64 + dir * 32 + h]);
;         const float dskip = INP(13)[l * 32 + h];
;         f32x4 Hacc[4];
; #pragma unroll
;         for (int j = 0; j < 4; ++j) Hacc[j] = (f32x4){0.f, 0.f, 0.f, 0.f};
;         for (int i = tid; i < 17408 / 4; i += 512) ((LAS unsigned*)L_H)[i] = 0u;
;         u32x4 pc[4], pb[4], px[2]; float pd0 = 0.f, pd1 = 0.f;
;     ...
;         SSD_ISSUE(0);
; #pragma unroll 1
;         for (int step = 0; step < 66; ++step) {
;             const int row0 = SSD_GC(step) * 128;
; #pragma unroll
;             for (int i = 0; i < 4; ++i) { *(LAS u32x4*)(L_C + wCB + i * 32 * 272) = pc[i]; *(LAS u32x4*)(L_B + wCB + i * 32 * 272) = pb[i]; }
; #pragma unroll
;             for (int i = 0; i < 2; ++i) *(LAS u32x4*)(L_X + wX + i * 64 * 144) = px[i];
.LBB0_95:
	s_cmp_lg_u32 s4, 0
	s_cselect_b64 s[70:71], -1, 0
	s_lshl_b32 s5, s46, 6
	s_add_i32 s0, s5, 0x49
	v_writelane_b32 v255, s0, 55
	s_lshl_b32 s94, s46, 1
	s_or_b32 s0, s5, 6
	s_or_b32 s3, s94, 1
	v_writelane_b32 v255, s0, 56
	s_lshl_b32 s0, s45, 2
	v_readlane_b32 s42, v254, 62
	v_readlane_b32 s43, v254, 63
	s_add_u32 s0, s42, s0
	s_addc_u32 s38, s43, 0
	s_lshl_b32 s42, s44, 2
	s_add_u32 s88, s0, s42
	s_addc_u32 s89, s38, 0
	s_lshl_b32 s0, s4, 12
	v_readlane_b32 s38, v254, 60
	s_add_u32 s0, s38, s0
	v_readlane_b32 s38, v254, 61
	s_addc_u32 s43, s38, 0
	s_lshl_b32 s38, s47, 1
	s_add_u32 s42, s0, s38
	s_addc_u32 s43, s43, 0
	v_lshl_add_u64 v[114:115], s[42:43], 0, v[160:161]
	v_readlane_b32 s42, v255, 8
	s_waitcnt vmcnt(11)
	v_mul_f32_e32 v41, 0x3fb8aa3b, v41
	v_readlane_b32 s43, v255, 9
	v_exp_f32_e32 v166, v41
	s_cmp_eq_u32 s4, 0
	v_cndmask_b32_e64 v41, 0, 1, s[42:43]
	v_readlane_b32 s42, v255, 6
	v_readlane_b32 s43, v255, 7
	v_readlane_b32 s44, v255, 12
	v_readlane_b32 s45, v255, 13
	v_cndmask_b32_e64 v42, 0, 1, s[42:43]
	s_cselect_b64 s[42:43], -1, 0
	v_cndmask_b32_e64 v41, v41, v42, s[42:43]
	v_cndmask_b32_e64 v42, 0, 1, s[44:45]
	v_readlane_b32 s44, v255, 10
	v_readlane_b32 s45, v255, 11
	v_and_b32_e32 v41, 1, v41
	v_readlane_b32 s60, v255, 38
	v_cndmask_b32_e64 v43, 0, 1, s[44:45]
	v_readlane_b32 s44, v255, 16
	v_readlane_b32 s45, v255, 17
	v_cndmask_b32_e64 v42, v42, v43, s[42:43]
	v_readlane_b32 s61, v255, 39
	v_cndmask_b32_e64 v43, 0, 1, s[44:45]
	v_readlane_b32 s44, v255, 14
	v_readlane_b32 s45, v255, 15
	v_readlane_b32 s62, v255, 42
	v_readlane_b32 s63, v255, 43
	v_cndmask_b32_e64 v44, 0, 1, s[44:45]
	v_readlane_b32 s44, v255, 20
	v_readlane_b32 s45, v255, 21
	v_cndmask_b32_e64 v43, v43, v44, s[42:43]
	v_readlane_b32 s64, v255, 46
	v_cndmask_b32_e64 v44, 0, 1, s[44:45]
	v_readlane_b32 s44, v255, 18
	v_readlane_b32 s45, v255, 19
	v_readlane_b32 s65, v255, 47
	v_readlane_b32 s66, v255, 50
	v_cndmask_b32_e64 v45, 0, 1, s[44:45]
	v_readlane_b32 s44, v255, 24
	v_readlane_b32 s45, v255, 25
	v_cndmask_b32_e64 v44, v44, v45, s[42:43]
	v_readlane_b32 s67, v255, 51
	v_cndmask_b32_e64 v45, 0, 1, s[44:45]
	v_readlane_b32 s44, v255, 22
	v_readlane_b32 s45, v255, 23
	s_mov_b32 s74, 0
	s_waitcnt vmcnt(10)
	v_mov_b32_e32 v111, v110
	v_cndmask_b32_e64 v46, 0, 1, s[44:45]
	v_readlane_b32 s44, v255, 28
	v_readlane_b32 s45, v255, 29
	v_cndmask_b32_e64 v45, v45, v46, s[42:43]
	s_movk_i32 s4, 0x48
	v_cndmask_b32_e64 v46, 0, 1, s[44:45]
	v_readlane_b32 s44, v255, 26
	v_readlane_b32 s45, v255, 27
	s_lshl_b32 s95, s1, 1
	s_mov_b32 s72, 0
	v_cndmask_b32_e64 v47, 0, 1, s[44:45]
	v_readlane_b32 s44, v255, 32
	v_readlane_b32 s45, v255, 33
	v_cndmask_b32_e64 v46, v46, v47, s[42:43]
	v_mov_b32_e32 v50, v40
	v_cndmask_b32_e64 v47, 0, 1, s[44:45]
	v_readlane_b32 s44, v255, 30
	v_readlane_b32 s45, v255, 31
	v_mov_b32_e32 v51, v40
	v_mov_b32_e32 v52, v40
	v_cndmask_b32_e64 v48, 0, 1, s[44:45]
	v_readlane_b32 s44, v255, 36
	v_readlane_b32 s45, v255, 37
	v_cndmask_b32_e64 v47, v47, v48, s[42:43]
	v_mov_b32_e32 v53, v40
	v_cndmask_b32_e64 v48, 0, 1, s[44:45]
	v_readlane_b32 s44, v255, 34
	v_readlane_b32 s45, v255, 35
	v_mov_b32_e32 v54, v40
	v_mov_b32_e32 v55, v40
	v_cndmask_b32_e64 v49, 0, 1, s[44:45]
	v_cmp_eq_u32_e64 s[44:45], 1, v41
	v_and_b32_e32 v41, 1, v42
	v_cmp_eq_u32_e64 s[46:47], 1, v41
	v_and_b32_e32 v41, 1, v43
	v_cmp_eq_u32_e64 s[48:49], 1, v41
	v_and_b32_e32 v41, 1, v44
	v_cmp_eq_u32_e64 s[50:51], 1, v41
	v_and_b32_e32 v41, 1, v45
	v_cmp_eq_u32_e64 s[52:53], 1, v41
	v_and_b32_e32 v41, 1, v46
	v_cndmask_b32_e64 v48, v48, v49, s[42:43]
	v_cmp_eq_u32_e64 s[54:55], 1, v41
	v_and_b32_e32 v41, 1, v47
	v_cmp_eq_u32_e64 s[56:57], 1, v41
	v_and_b32_e32 v41, 1, v48
	v_cmp_eq_u32_e64 s[58:59], 1, v41
	v_cndmask_b32_e64 v41, 0, 1, s[60:61]
	v_readlane_b32 s60, v255, 40
	v_readlane_b32 s61, v255, 41
	v_mov_b32_e32 v43, v40
	v_mov_b32_e32 v44, v40
	v_cndmask_b32_e64 v42, 0, 1, s[60:61]
	v_cndmask_b32_e64 v41, v42, v41, s[42:43]
	v_and_b32_e32 v41, 1, v41
	v_cmp_eq_u32_e64 s[60:61], 1, v41
	v_cndmask_b32_e64 v41, 0, 1, s[62:63]
	v_readlane_b32 s62, v255, 44
	v_readlane_b32 s63, v255, 45
	v_mov_b32_e32 v45, v40
	v_mov_b32_e32 v46, v40
	v_cndmask_b32_e64 v42, 0, 1, s[62:63]
	v_cndmask_b32_e64 v41, v42, v41, s[42:43]
	v_and_b32_e32 v41, 1, v41
	v_cmp_eq_u32_e64 s[62:63], 1, v41
	v_cndmask_b32_e64 v41, 0, 1, s[64:65]
	v_readlane_b32 s64, v255, 48
	v_readlane_b32 s65, v255, 49
	v_mov_b32_e32 v47, v40
	v_mov_b32_e32 v48, v40
	v_cndmask_b32_e64 v42, 0, 1, s[64:65]
	v_cndmask_b32_e64 v41, v42, v41, s[42:43]
	v_and_b32_e32 v41, 1, v41
	v_cmp_eq_u32_e64 s[64:65], 1, v41
	v_cndmask_b32_e64 v41, 0, 1, s[66:67]
	v_readlane_b32 s66, v255, 52
	v_readlane_b32 s67, v255, 53
	v_mov_b32_e32 v49, v40
	s_nop 0
	v_cndmask_b32_e64 v42, 0, 1, s[66:67]
	v_cndmask_b32_e64 v41, v42, v41, s[42:43]
	v_and_b32_e32 v41, 1, v41
	v_cmp_eq_u32_e64 s[66:67], 1, v41
	v_mov_b32_e32 v41, v40
	v_mov_b32_e32 v42, v40
	v_readfirstlane_b32 vcc_lo, v164
	v_and_b32_e32 v168, 15, v164
	v_bfe_u32 v169, v164, 4, 2
	v_lshlrev_b32_e32 v168, 13, v168
	s_lshr_b32 vcc_lo, vcc_lo, 6
	s_sub_i32 vcc_hi, 11, vcc_lo
	s_cmp_lt_u32 vcc_lo, 4
	s_cselect_b32 vcc_lo, vcc_lo, vcc_hi
	s_lshl_b32 vcc_lo, vcc_lo, 17
	v_lshl_add_u32 v168, v169, 4, v168
	v_add_u32_e32 v168, vcc_lo, v168
	v_mov_b32_e32 v169, 0
	s_add_u32 s90, s90, 0x1800
	s_addc_u32 s91, s91, 0
	v_lshl_add_u64 v[168:169], s[90:91], 0, v[168:169]
	global_load_dwordx4 v[0:3], v[168:169], off
	global_load_dwordx4 v[8:11], v[168:169], off offset:64
	global_load_dwordx4 v[16:19], v[168:169], off offset:128
	global_load_dwordx4 v[24:27], v[168:169], off offset:192
	s_waitcnt vmcnt(0)
	ds_write_b128 v144, v[4:7] offset:32768
	ds_write_b128 v144, v[12:15] offset:41984
	ds_write_b128 v144, v[20:23] offset:51200
	ds_write_b128 v144, v[28:31] offset:60416
	s_branch .LBB0_97

; #define LAS __attribute__((address_space(3)))
; __device__ __forceinline__ unsigned cvt_pk_bf16(float lo, float hi) { unsigned r; asm volatile("v_cvt_pk_bf16_f32 %0, %1, %2" : "=v"(r) : "v"(lo), "v"(hi)); return r; }
; #define MFMA16(a, b, c) __builtin_amdgcn_mfma_f32_16x16x32_bf16((a), (b), (c), 0, 0, 0)
; #define TRB(base, krow0, col0, t) __builtin_amdgcn_ds_read_tr16_b64_v4i16((LAS s16x4*)((base) + trB + ((krow0) + 4 * (t)) * 272 + (col0) * 2))
; #define TRX(base, krow0, col0, t) __builtin_amdgcn_ds_read_tr16_b64_v4i16((LAS s16x4*)((base) + trX + ((krow0) + 4 * (t)) * 144 + (col0) * 2))
; __device__ __forceinline__ void phase_C1(const Args& a, unsigned char* ws, const int bid, int l, LAS unsigned char* lds, int tid, int wave, int lane) {
;     ...
;             { const float etot = __expf(totp[0]);
; #pragma unroll
;               for (int j = 0; j < 4; ++j) Hacc[j] = Hacc[j] * etot;
; #pragma unroll
;               for (int s = 0; s < 4; ++s) { const s16x4 xlo = TRX(L_X, 32 * s, 16 * wr, 0), xhi = TRX(L_X, 32 * s, 16 * wr, 1);
;                   const f32x4 w0 = *(const LAS f32x4*)(wgt + s * 32 + fq * 8), w1 = *(const LAS f32x4*)(wgt + s * 32 + fq * 8 + 4);
;                   s16x4 blo[4], bhi[4];
; #pragma unroll
;                   for (int j = 0; j < 4; ++j) { blo[j] = TRB(L_B, 32 * s, 16 * (4 * wc + j), 0); bhi[j] = TRB(L_B, 32 * s, 16 * (4 * wc + j), 1); }
;                   __builtin_amdgcn_sched_barrier(0);
;                   const u32x2 xl = __builtin_bit_cast(u32x2, xlo), xh = __builtin_bit_cast(u32x2, xhi);
;                   u32x4 xs; xs.x = cvt_pk_bf16(bflo(xl.x) * w0.x, bfhi(xl.x) * w0.y); xs.y = cvt_pk_bf16(bflo(xl.y) * w0.z, bfhi(xl.y) * w0.w);
;                   xs.z = cvt_pk_bf16(bflo(xh.x) * w1.x, bfhi(xh.x) * w1.y); xs.w = cvt_pk_bf16(bflo(xh.y) * w1.z, bfhi(xh.y) * w1.w);
;                   const bf16x8 xq = __builtin_bit_cast(bf16x8, xs);
; #pragma unroll
;                   for (int j = 0; j < 4; ++j) { const bf16x8 bt = (bf16x8){blo[j].x, blo[j].y, blo[j].z, blo[j].w, bhi[j].x, bhi[j].y, bhi[j].z, bhi[j].w};
;                       Hacc[j] = MFMA16(bt, xq, Hacc[j]); }
;                   __builtin_amdgcn_sched_barrier(0); } }
.Lssd_ha_e:
	v_mov_b32_e32 v116, s87
	ds_read_b32 v116, v116
	s_waitcnt lgkmcnt(0)
	v_mul_f32_e32 v116, 0x3fb8aa3b, v116
	v_exp_f32_e32 v116, v116
	s_nop 0
	v_pk_mul_f32 v[42:43], v[42:43], v[116:117] op_sel_hi:[1,0]
	v_pk_mul_f32 v[40:41], v[40:41], v[116:117] op_sel_hi:[1,0]
	v_pk_mul_f32 v[46:47], v[46:47], v[116:117] op_sel_hi:[1,0]
	v_pk_mul_f32 v[44:45], v[44:45], v[116:117] op_sel_hi:[1,0]
	v_pk_mul_f32 v[50:51], v[50:51], v[116:117] op_sel_hi:[1,0]
	v_pk_mul_f32 v[48:49], v[48:49], v[116:117] op_sel_hi:[1,0]
	v_pk_mul_f32 v[54:55], v[54:55], v[116:117] op_sel_hi:[1,0]
	v_pk_mul_f32 v[52:53], v[52:53], v[116:117] op_sel_hi:[1,0]
	ds_read_b64_tr_b16 v[116:117], v140
	ds_read_b64_tr_b16 v[192:193], v140 offset:576
	ds_read_b128 v[168:171], v125
	ds_read_b128 v[172:175], v125 offset:16
	ds_read_b64_tr_b16 v[178:179], v141 offset:33920
	ds_read_b64_tr_b16 v[176:177], v141 offset:32768
	ds_read_b64_tr_b16 v[180:181], v141 offset:32800
	ds_read_b64_tr_b16 v[182:183], v141 offset:33952
	ds_read_b64_tr_b16 v[184:185], v141 offset:32832
	ds_read_b64_tr_b16 v[186:187], v141 offset:33984
	ds_read_b64_tr_b16 v[188:189], v141 offset:32864
	ds_read_b64_tr_b16 v[190:191], v141 offset:34016
	s_waitcnt lgkmcnt(11)
	v_lshlrev_b32_e32 v194, 16, v116
	v_and_b32_e32 v116, 0xffff0000, v116
	s_waitcnt lgkmcnt(9)
	v_mul_f32_e32 v168, v168, v194
	v_mul_f32_e32 v116, v169, v116
	v_cvt_pk_bf16_f32 v168, v168, v116
	v_lshlrev_b32_e32 v116, 16, v117
	v_and_b32_e32 v117, 0xffff0000, v117
	v_mul_f32_e32 v116, v170, v116
	v_mul_f32_e32 v117, v171, v117
	v_cvt_pk_bf16_f32 v169, v116, v117
	v_lshlrev_b32_e32 v116, 16, v192
	v_and_b32_e32 v117, 0xffff0000, v192
	s_waitcnt lgkmcnt(8)
	v_mul_f32_e32 v116, v172, v116
	v_mul_f32_e32 v117, v173, v117
	v_cvt_pk_bf16_f32 v170, v116, v117
	v_lshlrev_b32_e32 v116, 16, v193
	v_and_b32_e32 v117, 0xffff0000, v193
	v_mul_f32_e32 v116, v174, v116
	v_mul_f32_e32 v117, v175, v117
	v_cvt_pk_bf16_f32 v171, v116, v117
	s_waitcnt lgkmcnt(6)
	v_mfma_f32_16x16x32_bf16 v[40:43], v[176:179], v[168:171], v[40:43]
	s_waitcnt lgkmcnt(4)
	v_mfma_f32_16x16x32_bf16 v[44:47], v[180:183], v[168:171], v[44:47]
	s_waitcnt lgkmcnt(2)
	v_mfma_f32_16x16x32_bf16 v[48:51], v[184:187], v[168:171], v[48:51]
	s_waitcnt lgkmcnt(0)
	v_mfma_f32_16x16x32_bf16 v[52:55], v[188:191], v[168:171], v[52:55]
	ds_read_b128 v[168:171], v125 offset:128
	ds_read_b128 v[172:175], v125 offset:144
	ds_read_b64_tr_b16 v[116:117], v140 offset:4608
	ds_read_b64_tr_b16 v[192:193], v140 offset:5184
	ds_read_b64_tr_b16 v[176:177], v141 offset:41984
	ds_read_b64_tr_b16 v[180:181], v141 offset:42016
	ds_read_b64_tr_b16 v[178:179], v141 offset:43136
	ds_read_b64_tr_b16 v[182:183], v141 offset:43168
	ds_read_b64_tr_b16 v[184:185], v141 offset:42048
	ds_read_b64_tr_b16 v[188:189], v141 offset:42080
	ds_read_b64_tr_b16 v[186:187], v141 offset:43200
	ds_read_b64_tr_b16 v[190:191], v141 offset:43232
	s_waitcnt lgkmcnt(9)
	v_lshlrev_b32_e32 v194, 16, v116
	v_and_b32_e32 v116, 0xffff0000, v116
	v_mul_f32_e32 v168, v168, v194
	v_mul_f32_e32 v116, v169, v116
	v_cvt_pk_bf16_f32 v168, v168, v116
	v_lshlrev_b32_e32 v116, 16, v117
	v_and_b32_e32 v117, 0xffff0000, v117
	v_mul_f32_e32 v116, v170, v116
	v_mul_f32_e32 v117, v171, v117
	v_cvt_pk_bf16_f32 v169, v116, v117
	s_waitcnt lgkmcnt(8)
	v_lshlrev_b32_e32 v116, 16, v192
	v_and_b32_e32 v117, 0xffff0000, v192
	v_mul_f32_e32 v116, v172, v116
	v_mul_f32_e32 v117, v173, v117
	v_cvt_pk_bf16_f32 v170, v116, v117
	v_lshlrev_b32_e32 v116, 16, v193
	v_and_b32_e32 v117, 0xffff0000, v193
	v_mul_f32_e32 v116, v174, v116
	v_mul_f32_e32 v117, v175, v117
	v_cvt_pk_bf16_f32 v171, v116, v117
	s_waitcnt lgkmcnt(5)
	v_mfma_f32_16x16x32_bf16 v[40:43], v[176:179], v[168:171], v[40:43]
	s_waitcnt lgkmcnt(4)
	v_mfma_f32_16x16x32_bf16 v[44:47], v[180:183], v[168:171], v[44:47]
	s_waitcnt lgkmcnt(1)
	v_mfma_f32_16x16x32_bf16 v[48:51], v[184:187], v[168:171], v[48:51]
	s_waitcnt lgkmcnt(0)
; #define LAS __attribute__((address_space(3)))
; __device__ __forceinline__ unsigned cvt_pk_bf16(float lo, float hi) { unsigned r; asm volatile("v_cvt_pk_bf16_f32 %0, %1, %2" : "=v"(r) : "v"(lo), "v"(hi)); return r; }
; #define LDS_BARRIER() do { asm volatile("s_waitcnt lgkmcnt(0)" ::: "memory"); __builtin_amdgcn_s_barrier(); asm volatile("" ::: "memory"); } while (0)
; #define MFMA16(a, b, c) __builtin_amdgcn_mfma_f32_16x16x32_bf16((a), (b), (c), 0, 0, 0)
; #define TRB(base, krow0, col0, t) __builtin_amdgcn_ds_read_tr16_b64_v4i16((LAS s16x4*)((base) + trB + ((krow0) + 4 * (t)) * 272 + (col0) * 2))
; __device__ __forceinline__ void phase_C1(const Args& a, unsigned char* ws, const int bid, int l, LAS unsigned char* lds, int tid, int wave, int lane) {
;     ...
;               for (int s = 0; s < 4; ++s) { const s16x4 xlo = TRX(L_X, 32 * s, 16 * wr, 0), xhi = TRX(L_X, 32 * s, 16 * wr, 1);
;                   const f32x4 w0 = *(const LAS f32x4*)(wgt + s * 32 + fq * 8), w1 = *(const LAS f32x4*)(wgt + s * 32 + fq * 8 + 4);
;                   s16x4 blo[4], bhi[4];
; #pragma unroll
;                   for (int j = 0; j < 4; ++j) { blo[j] = TRB(L_B, 32 * s, 16 * (4 * wc + j), 0); bhi[j] = TRB(L_B, 32 * s, 16 * (4 * wc + j), 1); }
;                   __builtin_amdgcn_sched_barrier(0);
;                   const u32x2 xl = __builtin_bit_cast(u32x2, xlo), xh = __builtin_bit_cast(u32x2, xhi);
;                   u32x4 xs; xs.x = cvt_pk_bf16(bflo(xl.x) * w0.x, bfhi(xl.x) * w0.y); xs.y = cvt_pk_bf16(bflo(xl.y) * w0.z, bfhi(xl.y) * w0.w);
;                   xs.z = cvt_pk_bf16(bflo(xh.x) * w1.x, bfhi(xh.x) * w1.y); xs.w = cvt_pk_bf16(bflo(xh.y) * w1.z, bfhi(xh.y) * w1.w);
;                   const bf16x8 xq = __builtin_bit_cast(bf16x8, xs);
; #pragma unroll
;                   for (int j = 0; j < 4; ++j) { const bf16x8 bt = (bf16x8){blo[j].x, blo[j].y, blo[j].z, blo[j].w, bhi[j].x, bhi[j].y, bhi[j].z, bhi[j].w};
;                       Hacc[j] = MFMA16(bt, xq, Hacc[j]); }
;                   __builtin_amdgcn_sched_barrier(0); } }
;     ...
;             LDS_BARRIER();
; #pragma unroll
;             for (int j = 0; j < 4; ++j) { u32x2 o; o.x = cvt_pk_bf16(Hacc[j][0], Hacc[j][1]); o.y = cvt_pk_bf16(Hacc[j][2], Hacc[j][3]);
;                 *(LAS u32x2*)(L_H + (wr * 16 + fr) * 272 + ((4 * wc + j) * 16 + fq * 4) * 2) = o; }
	v_mfma_f32_16x16x32_bf16 v[52:55], v[188:191], v[168:171], v[52:55]
	ds_read_b128 v[168:171], v125 offset:256
	ds_read_b128 v[172:175], v125 offset:272
	ds_read_b64_tr_b16 v[116:117], v140 offset:9216
	ds_read_b64_tr_b16 v[192:193], v140 offset:9792
	ds_read_b64_tr_b16 v[176:177], v141 offset:51200
	ds_read_b64_tr_b16 v[180:181], v141 offset:51232
	ds_read_b64_tr_b16 v[178:179], v141 offset:52352
	ds_read_b64_tr_b16 v[182:183], v141 offset:52384
	ds_read_b64_tr_b16 v[184:185], v141 offset:51264
	ds_read_b64_tr_b16 v[188:189], v141 offset:51296
	ds_read_b64_tr_b16 v[186:187], v141 offset:52416
	ds_read_b64_tr_b16 v[190:191], v141 offset:52448
	s_waitcnt lgkmcnt(9)
	v_lshlrev_b32_e32 v194, 16, v116
	v_and_b32_e32 v116, 0xffff0000, v116
	v_mul_f32_e32 v168, v168, v194
	v_mul_f32_e32 v116, v169, v116
	v_cvt_pk_bf16_f32 v168, v168, v116
	v_lshlrev_b32_e32 v116, 16, v117
	v_and_b32_e32 v117, 0xffff0000, v117
	v_mul_f32_e32 v116, v170, v116
	v_mul_f32_e32 v117, v171, v117
	v_cvt_pk_bf16_f32 v169, v116, v117
	s_waitcnt lgkmcnt(8)
	v_lshlrev_b32_e32 v116, 16, v192
	v_and_b32_e32 v117, 0xffff0000, v192
	v_mul_f32_e32 v116, v172, v116
	v_mul_f32_e32 v117, v173, v117
	v_cvt_pk_bf16_f32 v170, v116, v117
	v_lshlrev_b32_e32 v116, 16, v193
	v_and_b32_e32 v117, 0xffff0000, v193
	v_mul_f32_e32 v116, v174, v116
	v_mul_f32_e32 v117, v175, v117
	v_cvt_pk_bf16_f32 v171, v116, v117
	s_waitcnt lgkmcnt(5)
	v_mfma_f32_16x16x32_bf16 v[40:43], v[176:179], v[168:171], v[40:43]
	s_waitcnt lgkmcnt(4)
	v_mfma_f32_16x16x32_bf16 v[44:47], v[180:183], v[168:171], v[44:47]
	s_waitcnt lgkmcnt(1)
	v_mfma_f32_16x16x32_bf16 v[48:51], v[184:187], v[168:171], v[48:51]
	s_waitcnt lgkmcnt(0)
	v_mfma_f32_16x16x32_bf16 v[52:55], v[188:191], v[168:171], v[52:55]
	ds_read_b128 v[168:171], v125 offset:384
	ds_read_b128 v[172:175], v125 offset:400
	ds_read_b64_tr_b16 v[116:117], v140 offset:13824
	ds_read_b64_tr_b16 v[192:193], v140 offset:14400
	ds_read_b64_tr_b16 v[176:177], v141 offset:60416
	ds_read_b64_tr_b16 v[180:181], v141 offset:60448
	ds_read_b64_tr_b16 v[178:179], v141 offset:61568
	ds_read_b64_tr_b16 v[182:183], v141 offset:61600
	ds_read_b64_tr_b16 v[184:185], v141 offset:60480
	ds_read_b64_tr_b16 v[188:189], v141 offset:60512
	ds_read_b64_tr_b16 v[186:187], v141 offset:61632
	ds_read_b64_tr_b16 v[190:191], v141 offset:61664
	s_waitcnt lgkmcnt(9)
	v_lshlrev_b32_e32 v194, 16, v116
	v_and_b32_e32 v116, 0xffff0000, v116
	v_mul_f32_e32 v168, v168, v194
	v_mul_f32_e32 v116, v169, v116
	v_cvt_pk_bf16_f32 v168, v168, v116
	v_lshlrev_b32_e32 v116, 16, v117
	v_and_b32_e32 v117, 0xffff0000, v117
	v_mul_f32_e32 v116, v170, v116
	v_mul_f32_e32 v117, v171, v117
	v_cvt_pk_bf16_f32 v169, v116, v117
	s_waitcnt lgkmcnt(8)
	v_lshlrev_b32_e32 v116, 16, v192
	v_and_b32_e32 v117, 0xffff0000, v192
	v_mul_f32_e32 v116, v172, v116
	v_mul_f32_e32 v117, v173, v117
	v_cvt_pk_bf16_f32 v170, v116, v117
	v_lshlrev_b32_e32 v116, 16, v193
	v_and_b32_e32 v117, 0xffff0000, v193
	v_mul_f32_e32 v116, v174, v116
	v_mul_f32_e32 v117, v175, v117
	v_cvt_pk_bf16_f32 v171, v116, v117
	s_waitcnt lgkmcnt(5)
	v_mfma_f32_16x16x32_bf16 v[40:43], v[176:179], v[168:171], v[40:43]
	s_waitcnt lgkmcnt(4)
	v_mfma_f32_16x16x32_bf16 v[44:47], v[180:183], v[168:171], v[44:47]
	s_waitcnt lgkmcnt(1)
	v_mfma_f32_16x16x32_bf16 v[48:51], v[184:187], v[168:171], v[48:51]
	s_waitcnt lgkmcnt(0)
	v_mfma_f32_16x16x32_bf16 v[52:55], v[188:191], v[168:171], v[52:55]
.Lssd_m_section:
	ds_read_b32 v117, v127
	ds_read_b32 v116, v128
	ds_read_b128 v[180:183], v130
	ds_read_b128 v[184:187], v131
	s_waitcnt lgkmcnt(0)
	s_barrier
	s_cmp_eq_u32 s4, 7
	s_cbranch_scc1 .Lssd_nofill
	s_waitcnt vmcnt(9)
	ds_write_b128 v144, v[4:7] offset:32768
	s_waitcnt vmcnt(8)
	ds_write_b128 v144, v[12:15] offset:41984
	s_waitcnt vmcnt(7)
	ds_write_b128 v144, v[20:23] offset:51200
	s_waitcnt vmcnt(6)
	ds_write_b128 v144, v[28:31] offset:60416
	v_cvt_pk_bf16_f32 v188, v40, v41
	v_cvt_pk_bf16_f32 v189, v42, v43
	ds_write_b64 v158, v[188:189]
	v_cvt_pk_bf16_f32 v188, v44, v45
	v_cvt_pk_bf16_f32 v189, v46, v47
	ds_write_b64 v158, v[188:189] offset:32
	v_cvt_pk_bf16_f32 v188, v48, v49
	v_cvt_pk_bf16_f32 v189, v50, v51
	ds_write_b64 v158, v[188:189] offset:64
	v_cvt_pk_bf16_f32 v188, v52, v53
	v_cvt_pk_bf16_f32 v189, v54, v55
	ds_write_b64 v158, v[188:189] offset:96

; #define LAS __attribute__((address_space(3)))
; __device__ __forceinline__ unsigned cvt_pk_bf16(float lo, float hi) { unsigned r; asm volatile("v_cvt_pk_bf16_f32 %0, %1, %2" : "=v"(r) : "v"(lo), "v"(hi)); return r; }
; #define MFMA16(a, b, c) __builtin_amdgcn_mfma_f32_16x16x32_bf16((a), (b), (c), 0, 0, 0)
; #define TRB(base, krow0, col0, t) __builtin_amdgcn_ds_read_tr16_b64_v4i16((LAS s16x4*)((base) + trB + ((krow0) + 4 * (t)) * 272 + (col0) * 2))
; #define TRX(base, krow0, col0, t) __builtin_amdgcn_ds_read_tr16_b64_v4i16((LAS s16x4*)((base) + trX + ((krow0) + 4 * (t)) * 144 + (col0) * 2))
; __device__ __forceinline__ void phase_C1(const Args& a, unsigned char* ws, const int bid, int l, LAS unsigned char* lds, int tid, int wave, int lane) {
;     ...
;             { const float etot = __expf(totp[0]);
; #pragma unroll
;               for (int j = 0; j < 4; ++j) Hacc[j] = Hacc[j] * etot;
; #pragma unroll
;               for (int s = 0; s < 4; ++s) { const s16x4 xlo = TRX(L_X, 32 * s, 16 * wr, 0), xhi = TRX(L_X, 32 * s, 16 * wr, 1);
;                   const f32x4 w0 = *(const LAS f32x4*)(wgt + s * 32 + fq * 8), w1 = *(const LAS f32x4*)(wgt + s * 32 + fq * 8 + 4);
;                   s16x4 blo[4], bhi[4];
; #pragma unroll
;                   for (int j = 0; j < 4; ++j) { blo[j] = TRB(L_B, 32 * s, 16 * (4 * wc + j), 0); bhi[j] = TRB(L_B, 32 * s, 16 * (4 * wc + j), 1); }
;                   __builtin_amdgcn_sched_barrier(0);
;                   const u32x2 xl = __builtin_bit_cast(u32x2, xlo), xh = __builtin_bit_cast(u32x2, xhi);
;                   u32x4 xs; xs.x = cvt_pk_bf16(bflo(xl.x) * w0.x, bfhi(xl.x) * w0.y); xs.y = cvt_pk_bf16(bflo(xl.y) * w0.z, bfhi(xl.y) * w0.w);
;                   xs.z = cvt_pk_bf16(bflo(xh.x) * w1.x, bfhi(xh.x) * w1.y); xs.w = cvt_pk_bf16(bflo(xh.y) * w1.z, bfhi(xh.y) * w1.w);
;                   const bf16x8 xq = __builtin_bit_cast(bf16x8, xs);
; #pragma unroll
;                   for (int j = 0; j < 4; ++j) { const bf16x8 bt = (bf16x8){blo[j].x, blo[j].y, blo[j].z, blo[j].w, bhi[j].x, bhi[j].y, bhi[j].z, bhi[j].w};
;                       Hacc[j] = MFMA16(bt, xq, Hacc[j]); }
;                   __builtin_amdgcn_sched_barrier(0); } }
.Lssd_alt_order:
	v_mov_b32_e32 v116, s87
	ds_read_b32 v116, v116
	s_waitcnt lgkmcnt(0)
	v_mul_f32_e32 v116, 0x3fb8aa3b, v116
	v_exp_f32_e32 v116, v116
	s_nop 0
	v_pk_mul_f32 v[42:43], v[42:43], v[116:117] op_sel_hi:[1,0]
	v_pk_mul_f32 v[40:41], v[40:41], v[116:117] op_sel_hi:[1,0]
	v_pk_mul_f32 v[46:47], v[46:47], v[116:117] op_sel_hi:[1,0]
	v_pk_mul_f32 v[44:45], v[44:45], v[116:117] op_sel_hi:[1,0]
	v_pk_mul_f32 v[50:51], v[50:51], v[116:117] op_sel_hi:[1,0]
	v_pk_mul_f32 v[48:49], v[48:49], v[116:117] op_sel_hi:[1,0]
	v_pk_mul_f32 v[54:55], v[54:55], v[116:117] op_sel_hi:[1,0]
	v_pk_mul_f32 v[52:53], v[52:53], v[116:117] op_sel_hi:[1,0]
	ds_read_b64_tr_b16 v[116:117], v140
	ds_read_b64_tr_b16 v[192:193], v140 offset:576
	ds_read_b128 v[168:171], v125
	ds_read_b128 v[172:175], v125 offset:16
	ds_read_b64_tr_b16 v[178:179], v141 offset:33920
	ds_read_b64_tr_b16 v[176:177], v141 offset:32768
	ds_read_b64_tr_b16 v[180:181], v141 offset:32800
	ds_read_b64_tr_b16 v[182:183], v141 offset:33952
	ds_read_b64_tr_b16 v[184:185], v141 offset:32832
	ds_read_b64_tr_b16 v[186:187], v141 offset:33984
	ds_read_b64_tr_b16 v[188:189], v141 offset:32864
	ds_read_b64_tr_b16 v[190:191], v141 offset:34016
	s_waitcnt lgkmcnt(11)
	v_lshlrev_b32_e32 v194, 16, v116
	v_and_b32_e32 v116, 0xffff0000, v116
	s_waitcnt lgkmcnt(9)
	v_mul_f32_e32 v168, v168, v194
	v_mul_f32_e32 v116, v169, v116
	v_cvt_pk_bf16_f32 v168, v168, v116
	v_lshlrev_b32_e32 v116, 16, v117
	v_and_b32_e32 v117, 0xffff0000, v117
	v_mul_f32_e32 v116, v170, v116
	v_mul_f32_e32 v117, v171, v117
	v_cvt_pk_bf16_f32 v169, v116, v117
	v_lshlrev_b32_e32 v116, 16, v192
	v_and_b32_e32 v117, 0xffff0000, v192
	s_waitcnt lgkmcnt(8)
	v_mul_f32_e32 v116, v172, v116
	v_mul_f32_e32 v117, v173, v117
	v_cvt_pk_bf16_f32 v170, v116, v117
	v_lshlrev_b32_e32 v116, 16, v193
	v_and_b32_e32 v117, 0xffff0000, v193
	v_mul_f32_e32 v116, v174, v116
	v_mul_f32_e32 v117, v175, v117
	v_cvt_pk_bf16_f32 v171, v116, v117
	s_waitcnt lgkmcnt(6)
	v_mfma_f32_16x16x32_bf16 v[40:43], v[176:179], v[168:171], v[40:43]
	s_waitcnt lgkmcnt(4)
	v_mfma_f32_16x16x32_bf16 v[44:47], v[180:183], v[168:171], v[44:47]
	s_waitcnt lgkmcnt(2)
	v_mfma_f32_16x16x32_bf16 v[48:51], v[184:187], v[168:171], v[48:51]
	s_waitcnt lgkmcnt(0)
	v_mfma_f32_16x16x32_bf16 v[52:55], v[188:191], v[168:171], v[52:55]
	ds_read_b128 v[168:171], v125 offset:128
	ds_read_b128 v[172:175], v125 offset:144
	ds_read_b64_tr_b16 v[116:117], v140 offset:4608
	ds_read_b64_tr_b16 v[192:193], v140 offset:5184
	ds_read_b64_tr_b16 v[176:177], v141 offset:41984
	ds_read_b64_tr_b16 v[180:181], v141 offset:42016
	ds_read_b64_tr_b16 v[178:179], v141 offset:43136
	ds_read_b64_tr_b16 v[182:183], v141 offset:43168
	ds_read_b64_tr_b16 v[184:185], v141 offset:42048
	ds_read_b64_tr_b16 v[188:189], v141 offset:42080
	ds_read_b64_tr_b16 v[186:187], v141 offset:43200
	ds_read_b64_tr_b16 v[190:191], v141 offset:43232
	s_waitcnt lgkmcnt(9)
	v_lshlrev_b32_e32 v194, 16, v116
	v_and_b32_e32 v116, 0xffff0000, v116
	v_mul_f32_e32 v168, v168, v194
	v_mul_f32_e32 v116, v169, v116
	v_cvt_pk_bf16_f32 v168, v168, v116
	v_lshlrev_b32_e32 v116, 16, v117
	v_and_b32_e32 v117, 0xffff0000, v117
	v_mul_f32_e32 v116, v170, v116
	v_mul_f32_e32 v117, v171, v117
	v_cvt_pk_bf16_f32 v169, v116, v117
	s_waitcnt lgkmcnt(8)
	v_lshlrev_b32_e32 v116, 16, v192
	v_and_b32_e32 v117, 0xffff0000, v192
	v_mul_f32_e32 v116, v172, v116
	v_mul_f32_e32 v117, v173, v117
	v_cvt_pk_bf16_f32 v170, v116, v117
	v_lshlrev_b32_e32 v116, 16, v193
	v_and_b32_e32 v117, 0xffff0000, v193
	v_mul_f32_e32 v116, v174, v116
	v_mul_f32_e32 v117, v175, v117
	v_cvt_pk_bf16_f32 v171, v116, v117
	s_waitcnt lgkmcnt(5)
; #define LAS __attribute__((address_space(3)))
; __device__ __forceinline__ unsigned cvt_pk_bf16(float lo, float hi) { unsigned r; asm volatile("v_cvt_pk_bf16_f32 %0, %1, %2" : "=v"(r) : "v"(lo), "v"(hi)); return r; }
; #define MFMA16(a, b, c) __builtin_amdgcn_mfma_f32_16x16x32_bf16((a), (b), (c), 0, 0, 0)
; #define TRB(base, krow0, col0, t) __builtin_amdgcn_ds_read_tr16_b64_v4i16((LAS s16x4*)((base) + trB + ((krow0) + 4 * (t)) * 272 + (col0) * 2))
; #define TRX(base, krow0, col0, t) __builtin_amdgcn_ds_read_tr16_b64_v4i16((LAS s16x4*)((base) + trX + ((krow0) + 4 * (t)) * 144 + (col0) * 2))
; __device__ __forceinline__ void phase_C1(const Args& a, unsigned char* ws, const int bid, int l, LAS unsigned char* lds, int tid, int wave, int lane) {
;     ...
;               for (int s = 0; s < 4; ++s) { const s16x4 xlo = TRX(L_X, 32 * s, 16 * wr, 0), xhi = TRX(L_X, 32 * s, 16 * wr, 1);
;                   const f32x4 w0 = *(const LAS f32x4*)(wgt + s * 32 + fq * 8), w1 = *(const LAS f32x4*)(wgt + s * 32 + fq * 8 + 4);
;                   s16x4 blo[4], bhi[4];
; #pragma unroll
;                   for (int j = 0; j < 4; ++j) { blo[j] = TRB(L_B, 32 * s, 16 * (4 * wc + j), 0); bhi[j] = TRB(L_B, 32 * s, 16 * (4 * wc + j), 1); }
;                   __builtin_amdgcn_sched_barrier(0);
;                   const u32x2 xl = __builtin_bit_cast(u32x2, xlo), xh = __builtin_bit_cast(u32x2, xhi);
;                   u32x4 xs; xs.x = cvt_pk_bf16(bflo(xl.x) * w0.x, bfhi(xl.x) * w0.y); xs.y = cvt_pk_bf16(bflo(xl.y) * w0.z, bfhi(xl.y) * w0.w);
;                   xs.z = cvt_pk_bf16(bflo(xh.x) * w1.x, bfhi(xh.x) * w1.y); xs.w = cvt_pk_bf16(bflo(xh.y) * w1.z, bfhi(xh.y) * w1.w);
;                   const bf16x8 xq = __builtin_bit_cast(bf16x8, xs);
; #pragma unroll
;                   for (int j = 0; j < 4; ++j) { const bf16x8 bt = (bf16x8){blo[j].x, blo[j].y, blo[j].z, blo[j].w, bhi[j].x, bhi[j].y, bhi[j].z, bhi[j].w};
;                       Hacc[j] = MFMA16(bt, xq, Hacc[j]); }
;                   __builtin_amdgcn_sched_barrier(0); } }
	v_mfma_f32_16x16x32_bf16 v[40:43], v[176:179], v[168:171], v[40:43]
	s_waitcnt lgkmcnt(4)
	v_mfma_f32_16x16x32_bf16 v[44:47], v[180:183], v[168:171], v[44:47]
	s_waitcnt lgkmcnt(1)
	v_mfma_f32_16x16x32_bf16 v[48:51], v[184:187], v[168:171], v[48:51]
	s_waitcnt lgkmcnt(0)
	v_mfma_f32_16x16x32_bf16 v[52:55], v[188:191], v[168:171], v[52:55]
	ds_read_b128 v[168:171], v125 offset:256
	ds_read_b128 v[172:175], v125 offset:272
	ds_read_b64_tr_b16 v[116:117], v140 offset:9216
	ds_read_b64_tr_b16 v[192:193], v140 offset:9792
	ds_read_b64_tr_b16 v[176:177], v141 offset:51200
	ds_read_b64_tr_b16 v[180:181], v141 offset:51232
	ds_read_b64_tr_b16 v[178:179], v141 offset:52352
	ds_read_b64_tr_b16 v[182:183], v141 offset:52384
	ds_read_b64_tr_b16 v[184:185], v141 offset:51264
	ds_read_b64_tr_b16 v[188:189], v141 offset:51296
	ds_read_b64_tr_b16 v[186:187], v141 offset:52416
	ds_read_b64_tr_b16 v[190:191], v141 offset:52448
	s_waitcnt lgkmcnt(9)
	v_lshlrev_b32_e32 v194, 16, v116
	v_and_b32_e32 v116, 0xffff0000, v116
	v_mul_f32_e32 v168, v168, v194
	v_mul_f32_e32 v116, v169, v116
	v_cvt_pk_bf16_f32 v168, v168, v116
	v_lshlrev_b32_e32 v116, 16, v117
	v_and_b32_e32 v117, 0xffff0000, v117
	v_mul_f32_e32 v116, v170, v116
	v_mul_f32_e32 v117, v171, v117
	v_cvt_pk_bf16_f32 v169, v116, v117
	s_waitcnt lgkmcnt(8)
	v_lshlrev_b32_e32 v116, 16, v192
	v_and_b32_e32 v117, 0xffff0000, v192
	v_mul_f32_e32 v116, v172, v116
	v_mul_f32_e32 v117, v173, v117
	v_cvt_pk_bf16_f32 v170, v116, v117
	v_lshlrev_b32_e32 v116, 16, v193
	v_and_b32_e32 v117, 0xffff0000, v193
	v_mul_f32_e32 v116, v174, v116
	v_mul_f32_e32 v117, v175, v117
	v_cvt_pk_bf16_f32 v171, v116, v117
	s_waitcnt lgkmcnt(5)
	v_mfma_f32_16x16x32_bf16 v[40:43], v[176:179], v[168:171], v[40:43]
	s_waitcnt lgkmcnt(4)
	v_mfma_f32_16x16x32_bf16 v[44:47], v[180:183], v[168:171], v[44:47]
	s_waitcnt lgkmcnt(1)
	v_mfma_f32_16x16x32_bf16 v[48:51], v[184:187], v[168:171], v[48:51]
	s_waitcnt lgkmcnt(0)
	v_mfma_f32_16x16x32_bf16 v[52:55], v[188:191], v[168:171], v[52:55]
	ds_read_b128 v[168:171], v125 offset:384
	ds_read_b128 v[172:175], v125 offset:400
	ds_read_b64_tr_b16 v[116:117], v140 offset:13824
	ds_read_b64_tr_b16 v[192:193], v140 offset:14400
	ds_read_b64_tr_b16 v[176:177], v141 offset:60416
	ds_read_b64_tr_b16 v[180:181], v141 offset:60448
	ds_read_b64_tr_b16 v[178:179], v141 offset:61568
	ds_read_b64_tr_b16 v[182:183], v141 offset:61600
	ds_read_b64_tr_b16 v[184:185], v141 offset:60480
	ds_read_b64_tr_b16 v[188:189], v141 offset:60512
	ds_read_b64_tr_b16 v[186:187], v141 offset:61632
	ds_read_b64_tr_b16 v[190:191], v141 offset:61664
	s_waitcnt lgkmcnt(9)
	v_lshlrev_b32_e32 v194, 16, v116
	v_and_b32_e32 v116, 0xffff0000, v116
	v_mul_f32_e32 v168, v168, v194
	v_mul_f32_e32 v116, v169, v116
	v_cvt_pk_bf16_f32 v168, v168, v116
	v_lshlrev_b32_e32 v116, 16, v117
	v_and_b32_e32 v117, 0xffff0000, v117
	v_mul_f32_e32 v116, v170, v116
	v_mul_f32_e32 v117, v171, v117
	v_cvt_pk_bf16_f32 v169, v116, v117
	s_waitcnt lgkmcnt(8)
	v_lshlrev_b32_e32 v116, 16, v192
	v_and_b32_e32 v117, 0xffff0000, v192
	v_mul_f32_e32 v116, v172, v116
	v_mul_f32_e32 v117, v173, v117
	v_cvt_pk_bf16_f32 v170, v116, v117
	v_lshlrev_b32_e32 v116, 16, v193
	v_and_b32_e32 v117, 0xffff0000, v193
	v_mul_f32_e32 v116, v174, v116
	v_mul_f32_e32 v117, v175, v117
	v_cvt_pk_bf16_f32 v171, v116, v117
	s_waitcnt lgkmcnt(5)
	v_mfma_f32_16x16x32_bf16 v[40:43], v[176:179], v[168:171], v[40:43]
	s_waitcnt lgkmcnt(4)
	v_mfma_f32_16x16x32_bf16 v[44:47], v[180:183], v[168:171], v[44:47]
	s_waitcnt lgkmcnt(1)
	v_mfma_f32_16x16x32_bf16 v[48:51], v[184:187], v[168:171], v[48:51]
	s_waitcnt lgkmcnt(0)
	v_mfma_f32_16x16x32_bf16 v[52:55], v[188:191], v[168:171], v[52:55]
	s_branch .Lssd_A_dispatch

; #define MFMA16(a, b, c) __builtin_amdgcn_mfma_f32_16x16x32_bf16((a), (b), (c), 0, 0, 0)
; __device__ __forceinline__ void phase_C1(const Args& a, unsigned char* ws, const int bid, int l, LAS unsigned char* lds, int tid, int wave, int lane) {
;     ...
;             {
;                 bf16x8 cqv[2], bq[2][4], hq[2][2];
;     ...
;                 SSD_LDH(0, 0);
; #pragma unroll
;                 for (int h2 = 0; h2 < 8; ++h2) { const int cb = h2 & 1, s_ = h2 >> 1, hf_ = h2 & 1;
;                     if (h2 < 7) SSD_LDH(cb ^ 1, h2 + 1);
;                     __builtin_amdgcn_sched_barrier(0);
; #pragma unroll
;                     for (int k = 0; k < 4; ++k) accA[4 * hf_ + k] = MFMA16(bq[cb][k], cqv[s_ & 1], accA[4 * hf_ + k]);
; #pragma unroll
;                     for (int p = 0; p < 2; ++p) accC[2 * hf_ + p] = MFMA16(hq[cb][p], cqv[s_ & 1], accC[2 * hf_ + p]);
;                     __builtin_amdgcn_sched_barrier(0); }
.Lssd_A_1111:
	ds_read_b128 v[56:59], v118 offset:32768
	ds_read_b128 v[60:63], v118 offset:37376
	ds_read_b128 v[64:67], v118 offset:41984
	ds_read_b128 v[68:71], v118 offset:46592
	ds_read_b128 v[76:79], v147
	ds_read_b128 v[80:83], v118 offset:51200
	ds_read_b128 v[84:87], v118 offset:55808
	ds_read_b128 v[88:91], v118 offset:60416
	ds_read_b128 v[92:95], v118 offset:65024
	ds_read_b128 v[96:99], v147 offset:4608
	ds_read_b128 v[100:103], v147 offset:9216
	ds_read_b128 v[168:171], v147 offset:13824
	s_waitcnt lgkmcnt(11)
	v_mfma_f32_16x16x32_bf16 v[56:59], v[56:59], v[0:3], 0
	s_waitcnt lgkmcnt(10)
	v_mfma_f32_16x16x32_bf16 v[60:63], v[60:63], v[0:3], 0
	s_waitcnt lgkmcnt(9)
	v_mfma_f32_16x16x32_bf16 v[64:67], v[64:67], v[0:3], 0
	s_waitcnt lgkmcnt(8)
	v_mfma_f32_16x16x32_bf16 v[68:71], v[68:71], v[0:3], 0
	s_waitcnt lgkmcnt(7)
	v_mfma_f32_16x16x32_bf16 v[76:79], v[76:79], v[0:3], 0
	s_waitcnt lgkmcnt(2)
	v_mfma_f32_16x16x32_bf16 v[96:99], v[96:99], v[0:3], 0
	ds_read_b128 v[172:175], v118 offset:32832
	ds_read_b128 v[176:179], v118 offset:37440
	ds_read_b128 v[180:183], v118 offset:42048
	ds_read_b128 v[184:187], v118 offset:46656
	ds_read_b128 v[212:215], v147 offset:64
	ds_read_b128 v[216:219], v147 offset:4672
	v_mfma_f32_16x16x32_bf16 v[80:83], v[80:83], v[0:3], 0
	v_mfma_f32_16x16x32_bf16 v[84:87], v[84:87], v[0:3], 0
	v_mfma_f32_16x16x32_bf16 v[88:91], v[88:91], v[0:3], 0
	v_mfma_f32_16x16x32_bf16 v[92:95], v[92:95], v[0:3], 0
	s_waitcnt lgkmcnt(7)
	v_mfma_f32_16x16x32_bf16 v[100:103], v[100:103], v[0:3], 0
	s_waitcnt lgkmcnt(6)
	v_mfma_f32_16x16x32_bf16 v[72:75], v[168:171], v[0:3], 0
	ds_read_b128 v[168:171], v118 offset:51264
	ds_read_b128 v[220:223], v118 offset:55872
	ds_read_b128 v[224:227], v118 offset:60480
	ds_read_b128 v[228:231], v118 offset:65088
	ds_read_b128 v[232:235], v147 offset:9280
	ds_read_b128 v[236:239], v147 offset:13888
	s_waitcnt lgkmcnt(11)
	v_mfma_f32_16x16x32_bf16 v[56:59], v[172:175], v[8:11], v[56:59]
	s_waitcnt lgkmcnt(10)
	v_mfma_f32_16x16x32_bf16 v[60:63], v[176:179], v[8:11], v[60:63]
	s_waitcnt lgkmcnt(9)
	v_mfma_f32_16x16x32_bf16 v[64:67], v[180:183], v[8:11], v[64:67]
	s_waitcnt lgkmcnt(8)
	v_mfma_f32_16x16x32_bf16 v[68:71], v[184:187], v[8:11], v[68:71]
	s_waitcnt lgkmcnt(7)
	v_mfma_f32_16x16x32_bf16 v[76:79], v[212:215], v[8:11], v[76:79]
	s_waitcnt lgkmcnt(6)
	v_mfma_f32_16x16x32_bf16 v[96:99], v[216:219], v[8:11], v[96:99]
	ds_read_b128 v[172:175], v118 offset:32896
	ds_read_b128 v[176:179], v118 offset:37504
	ds_read_b128 v[180:183], v118 offset:42112
	ds_read_b128 v[184:187], v118 offset:46720
	ds_read_b128 v[216:219], v147 offset:128
	ds_read_b128 v[240:243], v147 offset:4736
	s_waitcnt lgkmcnt(11)
	v_mfma_f32_16x16x32_bf16 v[80:83], v[168:171], v[8:11], v[80:83]
	s_waitcnt lgkmcnt(10)
	v_mfma_f32_16x16x32_bf16 v[84:87], v[220:223], v[8:11], v[84:87]
	s_waitcnt lgkmcnt(9)
	v_mfma_f32_16x16x32_bf16 v[88:91], v[224:227], v[8:11], v[88:91]
	s_waitcnt lgkmcnt(8)
	v_mfma_f32_16x16x32_bf16 v[92:95], v[228:231], v[8:11], v[92:95]
	s_waitcnt lgkmcnt(7)
	v_mfma_f32_16x16x32_bf16 v[100:103], v[232:235], v[8:11], v[100:103]
	s_waitcnt lgkmcnt(6)
	v_mfma_f32_16x16x32_bf16 v[72:75], v[236:239], v[8:11], v[72:75]
	ds_read_b128 v[168:171], v118 offset:51328
	ds_read_b128 v[188:191], v118 offset:55936
	ds_read_b128 v[220:223], v118 offset:60544
	ds_read_b128 v[224:227], v118 offset:65152
	ds_read_b128 v[228:231], v147 offset:9344
	ds_read_b128 v[232:235], v147 offset:13952
	s_waitcnt lgkmcnt(11)
	v_mfma_f32_16x16x32_bf16 v[56:59], v[172:175], v[16:19], v[56:59]
	s_waitcnt lgkmcnt(10)
	v_mfma_f32_16x16x32_bf16 v[60:63], v[176:179], v[16:19], v[60:63]
	s_waitcnt lgkmcnt(9)
	v_mfma_f32_16x16x32_bf16 v[64:67], v[180:183], v[16:19], v[64:67]
	s_waitcnt lgkmcnt(8)
	v_mfma_f32_16x16x32_bf16 v[68:71], v[184:187], v[16:19], v[68:71]
	s_waitcnt lgkmcnt(7)
	v_mfma_f32_16x16x32_bf16 v[76:79], v[216:219], v[16:19], v[76:79]
	s_waitcnt lgkmcnt(6)
	v_mfma_f32_16x16x32_bf16 v[172:175], v[240:243], v[16:19], v[96:99]
	s_nop 2
	ds_read_b128 v[96:99], v118 offset:32960
	ds_read_b128 v[176:179], v118 offset:37568
	ds_read_b128 v[180:183], v118 offset:42176
	ds_read_b128 v[184:187], v118 offset:46784
	ds_read_b128 v[236:239], v147 offset:192
	ds_read_b128 v[240:243], v147 offset:4800
	s_waitcnt lgkmcnt(11)
	v_mfma_f32_16x16x32_bf16 v[168:171], v[168:171], v[16:19], v[80:83]
	s_waitcnt lgkmcnt(10)
	v_mfma_f32_16x16x32_bf16 v[84:87], v[188:191], v[16:19], v[84:87]
	s_waitcnt lgkmcnt(9)
	v_mfma_f32_16x16x32_bf16 v[188:191], v[220:223], v[16:19], v[88:91]
	s_waitcnt lgkmcnt(8)
	v_mfma_f32_16x16x32_bf16 v[220:223], v[224:227], v[16:19], v[92:95]
	s_waitcnt lgkmcnt(7)
	v_mfma_f32_16x16x32_bf16 v[224:227], v[228:231], v[16:19], v[100:103]
	s_waitcnt lgkmcnt(6)
	v_mfma_f32_16x16x32_bf16 v[212:215], v[232:235], v[16:19], v[72:75]
	s_nop 2
	ds_read_b128 v[72:75], v118 offset:51392
	ds_read_b128 v[228:231], v118 offset:56000
	ds_read_b128 v[232:235], v118 offset:60608
	ds_read_b128 v[244:247], v118 offset:65216
	ds_read_b128 v[248:251], v147 offset:9408
	ds_read_b128 v[192:195], v147 offset:14016
	s_waitcnt lgkmcnt(11)
	v_mfma_f32_16x16x32_bf16 v[100:103], v[96:99], v[24:27], v[56:59]
	s_waitcnt lgkmcnt(10)
	v_mfma_f32_16x16x32_bf16 v[96:99], v[176:179], v[24:27], v[60:63]
	s_waitcnt lgkmcnt(9)
	v_mfma_f32_16x16x32_bf16 v[88:91], v[180:183], v[24:27], v[64:67]
	s_waitcnt lgkmcnt(8)
	v_mfma_f32_16x16x32_bf16 v[80:83], v[184:187], v[24:27], v[68:71]
	s_waitcnt lgkmcnt(7)
	v_mfma_f32_16x16x32_bf16 v[68:71], v[236:239], v[24:27], v[76:79]
	s_waitcnt lgkmcnt(6)
	v_mfma_f32_16x16x32_bf16 v[64:67], v[240:243], v[24:27], v[172:175]
	s_waitcnt lgkmcnt(5)
	v_mfma_f32_16x16x32_bf16 v[92:95], v[72:75], v[24:27], v[168:171]
	s_waitcnt lgkmcnt(4)
	v_mfma_f32_16x16x32_bf16 v[84:87], v[228:231], v[24:27], v[84:87]
	s_waitcnt lgkmcnt(3)
	v_mfma_f32_16x16x32_bf16 v[76:79], v[232:235], v[24:27], v[188:191]
	s_waitcnt lgkmcnt(2)
	v_mfma_f32_16x16x32_bf16 v[72:75], v[244:247], v[24:27], v[220:223]
	s_waitcnt lgkmcnt(1)
	v_mfma_f32_16x16x32_bf16 v[60:63], v[248:251], v[24:27], v[224:227]
	s_waitcnt lgkmcnt(0)
	v_mfma_f32_16x16x32_bf16 v[56:59], v[192:195], v[24:27], v[212:215]
	s_branch .Lssd_A_join
; #define MFMA16(a, b, c) __builtin_amdgcn_mfma_f32_16x16x32_bf16((a), (b), (c), 0, 0, 0)
; __device__ __forceinline__ void phase_C1(const Args& a, unsigned char* ws, const int bid, int l, LAS unsigned char* lds, int tid, int wave, int lane) {
;     ...
;             {
;                 bf16x8 cqv[2], bq[2][4], hq[2][2];
;     ...
;                 SSD_LDH(0, 0);
; #pragma unroll
;                 for (int h2 = 0; h2 < 8; ++h2) { const int cb = h2 & 1, s_ = h2 >> 1, hf_ = h2 & 1;
;                     if (h2 < 7) SSD_LDH(cb ^ 1, h2 + 1);
;                     __builtin_amdgcn_sched_barrier(0);
; #pragma unroll
;                     for (int k = 0; k < 4; ++k) accA[4 * hf_ + k] = MFMA16(bq[cb][k], cqv[s_ & 1], accA[4 * hf_ + k]);
; #pragma unroll
;                     for (int p = 0; p < 2; ++p) accC[2 * hf_ + p] = MFMA16(hq[cb][p], cqv[s_ & 1], accC[2 * hf_ + p]);
;                     __builtin_amdgcn_sched_barrier(0); }
.Lssd_A_1000:
	ds_read_b128 v[56:59], v118 offset:32768
	ds_read_b128 v[60:63], v118 offset:37376
	ds_read_b128 v[76:79], v147
	ds_read_b128 v[96:99], v147 offset:4608
	ds_read_b128 v[100:103], v147 offset:9216
	ds_read_b128 v[168:171], v147 offset:13824
	s_waitcnt lgkmcnt(5)
	v_mfma_f32_16x16x32_bf16 v[56:59], v[56:59], v[0:3], 0
	s_waitcnt lgkmcnt(4)
	v_mfma_f32_16x16x32_bf16 v[60:63], v[60:63], v[0:3], 0
	s_waitcnt lgkmcnt(3)
	v_mfma_f32_16x16x32_bf16 v[76:79], v[76:79], v[0:3], 0
	s_waitcnt lgkmcnt(2)
	v_mfma_f32_16x16x32_bf16 v[96:99], v[96:99], v[0:3], 0
	ds_read_b128 v[172:175], v118 offset:32832
	ds_read_b128 v[176:179], v118 offset:37440
	ds_read_b128 v[212:215], v147 offset:64
	ds_read_b128 v[216:219], v147 offset:4672
	s_waitcnt lgkmcnt(5)
	v_mfma_f32_16x16x32_bf16 v[100:103], v[100:103], v[0:3], 0
	s_waitcnt lgkmcnt(4)
	v_mfma_f32_16x16x32_bf16 v[72:75], v[168:171], v[0:3], 0
	ds_read_b128 v[232:235], v147 offset:9280
	ds_read_b128 v[236:239], v147 offset:13888
	s_waitcnt lgkmcnt(5)
	v_mfma_f32_16x16x32_bf16 v[56:59], v[172:175], v[8:11], v[56:59]
	s_waitcnt lgkmcnt(4)
	v_mfma_f32_16x16x32_bf16 v[60:63], v[176:179], v[8:11], v[60:63]
	s_waitcnt lgkmcnt(3)
	v_mfma_f32_16x16x32_bf16 v[76:79], v[212:215], v[8:11], v[76:79]
	s_waitcnt lgkmcnt(2)
	v_mfma_f32_16x16x32_bf16 v[96:99], v[216:219], v[8:11], v[96:99]
	ds_read_b128 v[172:175], v118 offset:32896
	ds_read_b128 v[176:179], v118 offset:37504
	ds_read_b128 v[216:219], v147 offset:128
	ds_read_b128 v[240:243], v147 offset:4736
	s_waitcnt lgkmcnt(5)
	v_mfma_f32_16x16x32_bf16 v[100:103], v[232:235], v[8:11], v[100:103]
	s_waitcnt lgkmcnt(4)
	v_mfma_f32_16x16x32_bf16 v[72:75], v[236:239], v[8:11], v[72:75]
	ds_read_b128 v[228:231], v147 offset:9344
	ds_read_b128 v[232:235], v147 offset:13952
	s_waitcnt lgkmcnt(5)
	v_mfma_f32_16x16x32_bf16 v[56:59], v[172:175], v[16:19], v[56:59]
	s_waitcnt lgkmcnt(4)
	v_mfma_f32_16x16x32_bf16 v[60:63], v[176:179], v[16:19], v[60:63]
	s_waitcnt lgkmcnt(3)
	v_mfma_f32_16x16x32_bf16 v[76:79], v[216:219], v[16:19], v[76:79]
	s_waitcnt lgkmcnt(2)
	v_mfma_f32_16x16x32_bf16 v[172:175], v[240:243], v[16:19], v[96:99]
	s_nop 2
	ds_read_b128 v[96:99], v118 offset:32960
	ds_read_b128 v[176:179], v118 offset:37568
	ds_read_b128 v[236:239], v147 offset:192
	ds_read_b128 v[240:243], v147 offset:4800
	s_waitcnt lgkmcnt(5)
	v_mfma_f32_16x16x32_bf16 v[224:227], v[228:231], v[16:19], v[100:103]
	s_waitcnt lgkmcnt(4)
	v_mfma_f32_16x16x32_bf16 v[212:215], v[232:235], v[16:19], v[72:75]
	s_nop 2
	ds_read_b128 v[248:251], v147 offset:9408
	ds_read_b128 v[192:195], v147 offset:14016
	s_waitcnt lgkmcnt(5)
	v_mfma_f32_16x16x32_bf16 v[100:103], v[96:99], v[24:27], v[56:59]
	s_waitcnt lgkmcnt(4)
	v_mfma_f32_16x16x32_bf16 v[96:99], v[176:179], v[24:27], v[60:63]
	s_waitcnt lgkmcnt(3)
	v_mfma_f32_16x16x32_bf16 v[68:71], v[236:239], v[24:27], v[76:79]
	s_waitcnt lgkmcnt(2)
	v_mfma_f32_16x16x32_bf16 v[64:67], v[240:243], v[24:27], v[172:175]
	s_waitcnt lgkmcnt(1)
	v_mfma_f32_16x16x32_bf16 v[60:63], v[248:251], v[24:27], v[224:227]
	s_waitcnt lgkmcnt(0)
	v_mfma_f32_16x16x32_bf16 v[56:59], v[192:195], v[24:27], v[212:215]
	s_branch .Lssd_A_join
.Lssd_A_1100:
	ds_read_b128 v[56:59], v118 offset:32768
	ds_read_b128 v[60:63], v118 offset:37376
	ds_read_b128 v[64:67], v118 offset:41984
	ds_read_b128 v[68:71], v118 offset:46592
	ds_read_b128 v[76:79], v147
	ds_read_b128 v[96:99], v147 offset:4608
	ds_read_b128 v[100:103], v147 offset:9216
	ds_read_b128 v[168:171], v147 offset:13824
	s_waitcnt lgkmcnt(7)
	v_mfma_f32_16x16x32_bf16 v[56:59], v[56:59], v[0:3], 0
	s_waitcnt lgkmcnt(6)
	v_mfma_f32_16x16x32_bf16 v[60:63], v[60:63], v[0:3], 0
	s_waitcnt lgkmcnt(5)
	v_mfma_f32_16x16x32_bf16 v[64:67], v[64:67], v[0:3], 0
	s_waitcnt lgkmcnt(4)
	v_mfma_f32_16x16x32_bf16 v[68:71], v[68:71], v[0:3], 0
	s_waitcnt lgkmcnt(3)
	v_mfma_f32_16x16x32_bf16 v[76:79], v[76:79], v[0:3], 0
	s_waitcnt lgkmcnt(2)
	v_mfma_f32_16x16x32_bf16 v[96:99], v[96:99], v[0:3], 0
	ds_read_b128 v[172:175], v118 offset:32832
	ds_read_b128 v[176:179], v118 offset:37440
	ds_read_b128 v[180:183], v118 offset:42048
	ds_read_b128 v[184:187], v118 offset:46656
	ds_read_b128 v[212:215], v147 offset:64
	ds_read_b128 v[216:219], v147 offset:4672
	s_waitcnt lgkmcnt(7)
	v_mfma_f32_16x16x32_bf16 v[100:103], v[100:103], v[0:3], 0
	s_waitcnt lgkmcnt(6)
	v_mfma_f32_16x16x32_bf16 v[72:75], v[168:171], v[0:3], 0
	ds_read_b128 v[232:235], v147 offset:9280
	ds_read_b128 v[236:239], v147 offset:13888
	s_waitcnt lgkmcnt(7)
	v_mfma_f32_16x16x32_bf16 v[56:59], v[172:175], v[8:11], v[56:59]
	s_waitcnt lgkmcnt(6)
	v_mfma_f32_16x16x32_bf16 v[60:63], v[176:179], v[8:11], v[60:63]
	s_waitcnt lgkmcnt(5)
	v_mfma_f32_16x16x32_bf16 v[64:67], v[180:183], v[8:11], v[64:67]
	s_waitcnt lgkmcnt(4)
	v_mfma_f32_16x16x32_bf16 v[68:71], v[184:187], v[8:11], v[68:71]
	s_waitcnt lgkmcnt(3)
	v_mfma_f32_16x16x32_bf16 v[76:79], v[212:215], v[8:11], v[76:79]
	s_waitcnt lgkmcnt(2)
	v_mfma_f32_16x16x32_bf16 v[96:99], v[216:219], v[8:11], v[96:99]
	ds_read_b128 v[172:175], v118 offset:32896
	ds_read_b128 v[176:179], v118 offset:37504
	ds_read_b128 v[180:183], v118 offset:42112
	ds_read_b128 v[184:187], v118 offset:46720
	ds_read_b128 v[216:219], v147 offset:128
	ds_read_b128 v[240:243], v147 offset:4736
	s_waitcnt lgkmcnt(7)
	v_mfma_f32_16x16x32_bf16 v[100:103], v[232:235], v[8:11], v[100:103]
	s_waitcnt lgkmcnt(6)
	v_mfma_f32_16x16x32_bf16 v[72:75], v[236:239], v[8:11], v[72:75]
	ds_read_b128 v[228:231], v147 offset:9344
	ds_read_b128 v[232:235], v147 offset:13952
	s_waitcnt lgkmcnt(7)
	v_mfma_f32_16x16x32_bf16 v[56:59], v[172:175], v[16:19], v[56:59]
	s_waitcnt lgkmcnt(6)
; #define MFMA16(a, b, c) __builtin_amdgcn_mfma_f32_16x16x32_bf16((a), (b), (c), 0, 0, 0)
; __device__ __forceinline__ void phase_C1(const Args& a, unsigned char* ws, const int bid, int l, LAS unsigned char* lds, int tid, int wave, int lane) {
;     ...
;             {
;                 bf16x8 cqv[2], bq[2][4], hq[2][2];
;     ...
;                 SSD_LDH(0, 0);
; #pragma unroll
;                 for (int h2 = 0; h2 < 8; ++h2) { const int cb = h2 & 1, s_ = h2 >> 1, hf_ = h2 & 1;
;                     if (h2 < 7) SSD_LDH(cb ^ 1, h2 + 1);
;                     __builtin_amdgcn_sched_barrier(0);
; #pragma unroll
;                     for (int k = 0; k < 4; ++k) accA[4 * hf_ + k] = MFMA16(bq[cb][k], cqv[s_ & 1], accA[4 * hf_ + k]);
; #pragma unroll
;                     for (int p = 0; p < 2; ++p) accC[2 * hf_ + p] = MFMA16(hq[cb][p], cqv[s_ & 1], accC[2 * hf_ + p]);
;                     __builtin_amdgcn_sched_barrier(0); }
	v_mfma_f32_16x16x32_bf16 v[60:63], v[176:179], v[16:19], v[60:63]
	s_waitcnt lgkmcnt(5)
	v_mfma_f32_16x16x32_bf16 v[64:67], v[180:183], v[16:19], v[64:67]
	s_waitcnt lgkmcnt(4)
	v_mfma_f32_16x16x32_bf16 v[68:71], v[184:187], v[16:19], v[68:71]
	s_waitcnt lgkmcnt(3)
	v_mfma_f32_16x16x32_bf16 v[76:79], v[216:219], v[16:19], v[76:79]
	s_waitcnt lgkmcnt(2)
	v_mfma_f32_16x16x32_bf16 v[172:175], v[240:243], v[16:19], v[96:99]
	s_nop 2
	ds_read_b128 v[96:99], v118 offset:32960
	ds_read_b128 v[176:179], v118 offset:37568
	ds_read_b128 v[180:183], v118 offset:42176
	ds_read_b128 v[184:187], v118 offset:46784
	ds_read_b128 v[236:239], v147 offset:192
	ds_read_b128 v[240:243], v147 offset:4800
	s_waitcnt lgkmcnt(7)
	v_mfma_f32_16x16x32_bf16 v[224:227], v[228:231], v[16:19], v[100:103]
	s_waitcnt lgkmcnt(6)
	v_mfma_f32_16x16x32_bf16 v[212:215], v[232:235], v[16:19], v[72:75]
	s_nop 2
	ds_read_b128 v[248:251], v147 offset:9408
	ds_read_b128 v[192:195], v147 offset:14016
	s_waitcnt lgkmcnt(7)
	v_mfma_f32_16x16x32_bf16 v[100:103], v[96:99], v[24:27], v[56:59]
	s_waitcnt lgkmcnt(6)
	v_mfma_f32_16x16x32_bf16 v[96:99], v[176:179], v[24:27], v[60:63]
	s_waitcnt lgkmcnt(5)
	v_mfma_f32_16x16x32_bf16 v[88:91], v[180:183], v[24:27], v[64:67]
	s_waitcnt lgkmcnt(4)
	v_mfma_f32_16x16x32_bf16 v[80:83], v[184:187], v[24:27], v[68:71]
	s_waitcnt lgkmcnt(3)
	v_mfma_f32_16x16x32_bf16 v[68:71], v[236:239], v[24:27], v[76:79]
	s_waitcnt lgkmcnt(2)
	v_mfma_f32_16x16x32_bf16 v[64:67], v[240:243], v[24:27], v[172:175]
	s_waitcnt lgkmcnt(1)
	v_mfma_f32_16x16x32_bf16 v[60:63], v[248:251], v[24:27], v[224:227]
	s_waitcnt lgkmcnt(0)
	v_mfma_f32_16x16x32_bf16 v[56:59], v[192:195], v[24:27], v[212:215]
	s_branch .Lssd_A_join
.Lssd_A_1110:
	ds_read_b128 v[56:59], v118 offset:32768
	ds_read_b128 v[60:63], v118 offset:37376
	ds_read_b128 v[64:67], v118 offset:41984
	ds_read_b128 v[68:71], v118 offset:46592
	ds_read_b128 v[76:79], v147
	ds_read_b128 v[80:83], v118 offset:51200
	ds_read_b128 v[84:87], v118 offset:55808
	ds_read_b128 v[96:99], v147 offset:4608
	ds_read_b128 v[100:103], v147 offset:9216
	ds_read_b128 v[168:171], v147 offset:13824
	s_waitcnt lgkmcnt(9)
	v_mfma_f32_16x16x32_bf16 v[56:59], v[56:59], v[0:3], 0
	s_waitcnt lgkmcnt(8)
	v_mfma_f32_16x16x32_bf16 v[60:63], v[60:63], v[0:3], 0
	s_waitcnt lgkmcnt(7)
	v_mfma_f32_16x16x32_bf16 v[64:67], v[64:67], v[0:3], 0
	s_waitcnt lgkmcnt(6)
	v_mfma_f32_16x16x32_bf16 v[68:71], v[68:71], v[0:3], 0
	s_waitcnt lgkmcnt(5)
	v_mfma_f32_16x16x32_bf16 v[76:79], v[76:79], v[0:3], 0
	s_waitcnt lgkmcnt(2)
	v_mfma_f32_16x16x32_bf16 v[96:99], v[96:99], v[0:3], 0
	ds_read_b128 v[172:175], v118 offset:32832
	ds_read_b128 v[176:179], v118 offset:37440
	ds_read_b128 v[180:183], v118 offset:42048
	ds_read_b128 v[184:187], v118 offset:46656
	ds_read_b128 v[212:215], v147 offset:64
	ds_read_b128 v[216:219], v147 offset:4672
	v_mfma_f32_16x16x32_bf16 v[80:83], v[80:83], v[0:3], 0
	v_mfma_f32_16x16x32_bf16 v[84:87], v[84:87], v[0:3], 0
	s_waitcnt lgkmcnt(7)
	v_mfma_f32_16x16x32_bf16 v[100:103], v[100:103], v[0:3], 0
	s_waitcnt lgkmcnt(6)
	v_mfma_f32_16x16x32_bf16 v[72:75], v[168:171], v[0:3], 0
	ds_read_b128 v[168:171], v118 offset:51264
	ds_read_b128 v[220:223], v118 offset:55872
	ds_read_b128 v[232:235], v147 offset:9280
	ds_read_b128 v[236:239], v147 offset:13888
	s_waitcnt lgkmcnt(9)
	v_mfma_f32_16x16x32_bf16 v[56:59], v[172:175], v[8:11], v[56:59]
	s_waitcnt lgkmcnt(8)
	v_mfma_f32_16x16x32_bf16 v[60:63], v[176:179], v[8:11], v[60:63]
	s_waitcnt lgkmcnt(7)
	v_mfma_f32_16x16x32_bf16 v[64:67], v[180:183], v[8:11], v[64:67]
	s_waitcnt lgkmcnt(6)
	v_mfma_f32_16x16x32_bf16 v[68:71], v[184:187], v[8:11], v[68:71]
	s_waitcnt lgkmcnt(5)
	v_mfma_f32_16x16x32_bf16 v[76:79], v[212:215], v[8:11], v[76:79]
	s_waitcnt lgkmcnt(4)
	v_mfma_f32_16x16x32_bf16 v[96:99], v[216:219], v[8:11], v[96:99]
	ds_read_b128 v[172:175], v118 offset:32896
	ds_read_b128 v[176:179], v118 offset:37504
	ds_read_b128 v[180:183], v118 offset:42112
	ds_read_b128 v[184:187], v118 offset:46720
	ds_read_b128 v[216:219], v147 offset:128
	ds_read_b128 v[240:243], v147 offset:4736
	s_waitcnt lgkmcnt(9)
	v_mfma_f32_16x16x32_bf16 v[80:83], v[168:171], v[8:11], v[80:83]
	s_waitcnt lgkmcnt(8)
	v_mfma_f32_16x16x32_bf16 v[84:87], v[220:223], v[8:11], v[84:87]
	s_waitcnt lgkmcnt(7)
	v_mfma_f32_16x16x32_bf16 v[100:103], v[232:235], v[8:11], v[100:103]
	s_waitcnt lgkmcnt(6)
	v_mfma_f32_16x16x32_bf16 v[72:75], v[236:239], v[8:11], v[72:75]
	ds_read_b128 v[168:171], v118 offset:51328
	ds_read_b128 v[188:191], v118 offset:55936
	ds_read_b128 v[228:231], v147 offset:9344
	ds_read_b128 v[232:235], v147 offset:13952
	s_waitcnt lgkmcnt(9)
	v_mfma_f32_16x16x32_bf16 v[56:59], v[172:175], v[16:19], v[56:59]
	s_waitcnt lgkmcnt(8)
	v_mfma_f32_16x16x32_bf16 v[60:63], v[176:179], v[16:19], v[60:63]
	s_waitcnt lgkmcnt(7)
	v_mfma_f32_16x16x32_bf16 v[64:67], v[180:183], v[16:19], v[64:67]
	s_waitcnt lgkmcnt(6)
	v_mfma_f32_16x16x32_bf16 v[68:71], v[184:187], v[16:19], v[68:71]
	s_waitcnt lgkmcnt(5)
	v_mfma_f32_16x16x32_bf16 v[76:79], v[216:219], v[16:19], v[76:79]
	s_waitcnt lgkmcnt(4)
	v_mfma_f32_16x16x32_bf16 v[172:175], v[240:243], v[16:19], v[96:99]
	s_nop 2
	ds_read_b128 v[96:99], v118 offset:32960
	ds_read_b128 v[176:179], v118 offset:37568
	ds_read_b128 v[180:183], v118 offset:42176
	ds_read_b128 v[184:187], v118 offset:46784
	ds_read_b128 v[236:239], v147 offset:192
	ds_read_b128 v[240:243], v147 offset:4800
	s_waitcnt lgkmcnt(9)
	v_mfma_f32_16x16x32_bf16 v[168:171], v[168:171], v[16:19], v[80:83]
	s_waitcnt lgkmcnt(8)
	v_mfma_f32_16x16x32_bf16 v[84:87], v[188:191], v[16:19], v[84:87]
	s_waitcnt lgkmcnt(7)
	v_mfma_f32_16x16x32_bf16 v[224:227], v[228:231], v[16:19], v[100:103]
	s_waitcnt lgkmcnt(6)
	v_mfma_f32_16x16x32_bf16 v[212:215], v[232:235], v[16:19], v[72:75]
	s_nop 2
	ds_read_b128 v[72:75], v118 offset:51392
	ds_read_b128 v[228:231], v118 offset:56000
	ds_read_b128 v[248:251], v147 offset:9408
	ds_read_b128 v[192:195], v147 offset:14016
	s_waitcnt lgkmcnt(9)
	v_mfma_f32_16x16x32_bf16 v[100:103], v[96:99], v[24:27], v[56:59]
	s_waitcnt lgkmcnt(8)
	v_mfma_f32_16x16x32_bf16 v[96:99], v[176:179], v[24:27], v[60:63]
	s_waitcnt lgkmcnt(7)
	v_mfma_f32_16x16x32_bf16 v[88:91], v[180:183], v[24:27], v[64:67]
	s_waitcnt lgkmcnt(6)
	v_mfma_f32_16x16x32_bf16 v[80:83], v[184:187], v[24:27], v[68:71]
	s_waitcnt lgkmcnt(5)
	v_mfma_f32_16x16x32_bf16 v[68:71], v[236:239], v[24:27], v[76:79]
	s_waitcnt lgkmcnt(4)
	v_mfma_f32_16x16x32_bf16 v[64:67], v[240:243], v[24:27], v[172:175]
	s_waitcnt lgkmcnt(3)
	v_mfma_f32_16x16x32_bf16 v[92:95], v[72:75], v[24:27], v[168:171]
	s_waitcnt lgkmcnt(2)
	v_mfma_f32_16x16x32_bf16 v[84:87], v[228:231], v[24:27], v[84:87]
	s_waitcnt lgkmcnt(1)
	v_mfma_f32_16x16x32_bf16 v[60:63], v[248:251], v[24:27], v[224:227]
	s_waitcnt lgkmcnt(0)
	v_mfma_f32_16x16x32_bf16 v[56:59], v[192:195], v[24:27], v[212:215]
	s_branch .Lssd_A_join
; #define MFMA16(a, b, c) __builtin_amdgcn_mfma_f32_16x16x32_bf16((a), (b), (c), 0, 0, 0)
; __device__ __forceinline__ void phase_C1(const Args& a, unsigned char* ws, const int bid, int l, LAS unsigned char* lds, int tid, int wave, int lane) {
;     ...
;             {
;                 bf16x8 cqv[2], bq[2][4], hq[2][2];
;     ...
;                 SSD_LDH(0, 0);
; #pragma unroll
;                 for (int h2 = 0; h2 < 8; ++h2) { const int cb = h2 & 1, s_ = h2 >> 1, hf_ = h2 & 1;
;                     if (h2 < 7) SSD_LDH(cb ^ 1, h2 + 1);
;                     __builtin_amdgcn_sched_barrier(0);
; #pragma unroll
;                     for (int k = 0; k < 4; ++k) accA[4 * hf_ + k] = MFMA16(bq[cb][k], cqv[s_ & 1], accA[4 * hf_ + k]);
; #pragma unroll
;                     for (int p = 0; p < 2; ++p) accC[2 * hf_ + p] = MFMA16(hq[cb][p], cqv[s_ & 1], accC[2 * hf_ + p]);
;                     __builtin_amdgcn_sched_barrier(0); }
.Lssd_A_0111:
	ds_read_b128 v[64:67], v118 offset:41984
	ds_read_b128 v[68:71], v118 offset:46592
	ds_read_b128 v[76:79], v147
	ds_read_b128 v[80:83], v118 offset:51200
	ds_read_b128 v[84:87], v118 offset:55808
	ds_read_b128 v[88:91], v118 offset:60416
	ds_read_b128 v[92:95], v118 offset:65024
	ds_read_b128 v[96:99], v147 offset:4608
	ds_read_b128 v[100:103], v147 offset:9216
	ds_read_b128 v[168:171], v147 offset:13824
	s_waitcnt lgkmcnt(9)
	v_mfma_f32_16x16x32_bf16 v[64:67], v[64:67], v[0:3], 0
	s_waitcnt lgkmcnt(8)
	v_mfma_f32_16x16x32_bf16 v[68:71], v[68:71], v[0:3], 0
	s_waitcnt lgkmcnt(7)
	v_mfma_f32_16x16x32_bf16 v[76:79], v[76:79], v[0:3], 0
	s_waitcnt lgkmcnt(2)
	v_mfma_f32_16x16x32_bf16 v[96:99], v[96:99], v[0:3], 0
	ds_read_b128 v[180:183], v118 offset:42048
	ds_read_b128 v[184:187], v118 offset:46656
	ds_read_b128 v[212:215], v147 offset:64
	ds_read_b128 v[216:219], v147 offset:4672
	v_mfma_f32_16x16x32_bf16 v[80:83], v[80:83], v[0:3], 0
	v_mfma_f32_16x16x32_bf16 v[84:87], v[84:87], v[0:3], 0
	v_mfma_f32_16x16x32_bf16 v[88:91], v[88:91], v[0:3], 0
	v_mfma_f32_16x16x32_bf16 v[92:95], v[92:95], v[0:3], 0
	s_waitcnt lgkmcnt(5)
	v_mfma_f32_16x16x32_bf16 v[100:103], v[100:103], v[0:3], 0
	s_waitcnt lgkmcnt(4)
	v_mfma_f32_16x16x32_bf16 v[72:75], v[168:171], v[0:3], 0
	ds_read_b128 v[168:171], v118 offset:51264
	ds_read_b128 v[220:223], v118 offset:55872
	ds_read_b128 v[224:227], v118 offset:60480
	ds_read_b128 v[228:231], v118 offset:65088
	ds_read_b128 v[232:235], v147 offset:9280
	ds_read_b128 v[236:239], v147 offset:13888
	s_waitcnt lgkmcnt(9)
	v_mfma_f32_16x16x32_bf16 v[64:67], v[180:183], v[8:11], v[64:67]
	s_waitcnt lgkmcnt(8)
	v_mfma_f32_16x16x32_bf16 v[68:71], v[184:187], v[8:11], v[68:71]
	s_waitcnt lgkmcnt(7)
	v_mfma_f32_16x16x32_bf16 v[76:79], v[212:215], v[8:11], v[76:79]
	s_waitcnt lgkmcnt(6)
	v_mfma_f32_16x16x32_bf16 v[96:99], v[216:219], v[8:11], v[96:99]
	ds_read_b128 v[180:183], v118 offset:42112
	ds_read_b128 v[184:187], v118 offset:46720
	ds_read_b128 v[216:219], v147 offset:128
	ds_read_b128 v[240:243], v147 offset:4736
	s_waitcnt lgkmcnt(9)
	v_mfma_f32_16x16x32_bf16 v[80:83], v[168:171], v[8:11], v[80:83]
	s_waitcnt lgkmcnt(8)
	v_mfma_f32_16x16x32_bf16 v[84:87], v[220:223], v[8:11], v[84:87]
	s_waitcnt lgkmcnt(7)
	v_mfma_f32_16x16x32_bf16 v[88:91], v[224:227], v[8:11], v[88:91]
	s_waitcnt lgkmcnt(6)
	v_mfma_f32_16x16x32_bf16 v[92:95], v[228:231], v[8:11], v[92:95]
	s_waitcnt lgkmcnt(5)
	v_mfma_f32_16x16x32_bf16 v[100:103], v[232:235], v[8:11], v[100:103]
	s_waitcnt lgkmcnt(4)
	v_mfma_f32_16x16x32_bf16 v[72:75], v[236:239], v[8:11], v[72:75]
	ds_read_b128 v[168:171], v118 offset:51328
	ds_read_b128 v[188:191], v118 offset:55936
	ds_read_b128 v[220:223], v118 offset:60544
	ds_read_b128 v[224:227], v118 offset:65152
	ds_read_b128 v[228:231], v147 offset:9344
	ds_read_b128 v[232:235], v147 offset:13952
	s_waitcnt lgkmcnt(9)
	v_mfma_f32_16x16x32_bf16 v[64:67], v[180:183], v[16:19], v[64:67]
	s_waitcnt lgkmcnt(8)
	v_mfma_f32_16x16x32_bf16 v[68:71], v[184:187], v[16:19], v[68:71]
	s_waitcnt lgkmcnt(7)
	v_mfma_f32_16x16x32_bf16 v[76:79], v[216:219], v[16:19], v[76:79]
	s_waitcnt lgkmcnt(6)
	v_mfma_f32_16x16x32_bf16 v[172:175], v[240:243], v[16:19], v[96:99]
	s_nop 2
	ds_read_b128 v[180:183], v118 offset:42176
	ds_read_b128 v[184:187], v118 offset:46784
	ds_read_b128 v[236:239], v147 offset:192
	ds_read_b128 v[240:243], v147 offset:4800
	s_waitcnt lgkmcnt(9)
	v_mfma_f32_16x16x32_bf16 v[168:171], v[168:171], v[16:19], v[80:83]
	s_waitcnt lgkmcnt(8)
	v_mfma_f32_16x16x32_bf16 v[84:87], v[188:191], v[16:19], v[84:87]
	s_waitcnt lgkmcnt(7)
	v_mfma_f32_16x16x32_bf16 v[188:191], v[220:223], v[16:19], v[88:91]
	s_waitcnt lgkmcnt(6)
	v_mfma_f32_16x16x32_bf16 v[220:223], v[224:227], v[16:19], v[92:95]
	s_waitcnt lgkmcnt(5)
	v_mfma_f32_16x16x32_bf16 v[224:227], v[228:231], v[16:19], v[100:103]
	s_waitcnt lgkmcnt(4)
	v_mfma_f32_16x16x32_bf16 v[212:215], v[232:235], v[16:19], v[72:75]
	s_nop 2
	ds_read_b128 v[72:75], v118 offset:51392
	ds_read_b128 v[228:231], v118 offset:56000
	ds_read_b128 v[232:235], v118 offset:60608
	ds_read_b128 v[244:247], v118 offset:65216
	ds_read_b128 v[248:251], v147 offset:9408
	ds_read_b128 v[192:195], v147 offset:14016
	s_waitcnt lgkmcnt(9)
	v_mfma_f32_16x16x32_bf16 v[88:91], v[180:183], v[24:27], v[64:67]
	s_waitcnt lgkmcnt(8)
	v_mfma_f32_16x16x32_bf16 v[80:83], v[184:187], v[24:27], v[68:71]
	s_waitcnt lgkmcnt(7)
	v_mfma_f32_16x16x32_bf16 v[68:71], v[236:239], v[24:27], v[76:79]
	s_waitcnt lgkmcnt(6)
	v_mfma_f32_16x16x32_bf16 v[64:67], v[240:243], v[24:27], v[172:175]
	s_waitcnt lgkmcnt(5)
	v_mfma_f32_16x16x32_bf16 v[92:95], v[72:75], v[24:27], v[168:171]
	s_waitcnt lgkmcnt(4)
	v_mfma_f32_16x16x32_bf16 v[84:87], v[228:231], v[24:27], v[84:87]
	s_waitcnt lgkmcnt(3)
	v_mfma_f32_16x16x32_bf16 v[76:79], v[232:235], v[24:27], v[188:191]
	s_waitcnt lgkmcnt(2)
	v_mfma_f32_16x16x32_bf16 v[72:75], v[244:247], v[24:27], v[220:223]
	s_waitcnt lgkmcnt(1)
	v_mfma_f32_16x16x32_bf16 v[60:63], v[248:251], v[24:27], v[224:227]
	s_waitcnt lgkmcnt(0)
	v_mfma_f32_16x16x32_bf16 v[56:59], v[192:195], v[24:27], v[212:215]
	s_branch .Lssd_A_join
; #define MFMA16(a, b, c) __builtin_amdgcn_mfma_f32_16x16x32_bf16((a), (b), (c), 0, 0, 0)
; __device__ __forceinline__ void phase_C1(const Args& a, unsigned char* ws, const int bid, int l, LAS unsigned char* lds, int tid, int wave, int lane) {
;     ...
;             {
;                 bf16x8 cqv[2], bq[2][4], hq[2][2];
;     ...
;                 SSD_LDH(0, 0);
; #pragma unroll
;                 for (int h2 = 0; h2 < 8; ++h2) { const int cb = h2 & 1, s_ = h2 >> 1, hf_ = h2 & 1;
;                     if (h2 < 7) SSD_LDH(cb ^ 1, h2 + 1);
;                     __builtin_amdgcn_sched_barrier(0);
; #pragma unroll
;                     for (int k = 0; k < 4; ++k) accA[4 * hf_ + k] = MFMA16(bq[cb][k], cqv[s_ & 1], accA[4 * hf_ + k]);
; #pragma unroll
;                     for (int p = 0; p < 2; ++p) accC[2 * hf_ + p] = MFMA16(hq[cb][p], cqv[s_ & 1], accC[2 * hf_ + p]);
;                     __builtin_amdgcn_sched_barrier(0); }
.Lssd_A_0011:
	ds_read_b128 v[76:79], v147
	ds_read_b128 v[80:83], v118 offset:51200
	ds_read_b128 v[84:87], v118 offset:55808
	ds_read_b128 v[88:91], v118 offset:60416
	ds_read_b128 v[92:95], v118 offset:65024
	ds_read_b128 v[96:99], v147 offset:4608
	ds_read_b128 v[100:103], v147 offset:9216
	ds_read_b128 v[168:171], v147 offset:13824
	s_waitcnt lgkmcnt(7)
	v_mfma_f32_16x16x32_bf16 v[76:79], v[76:79], v[0:3], 0
	s_waitcnt lgkmcnt(2)
	v_mfma_f32_16x16x32_bf16 v[96:99], v[96:99], v[0:3], 0
	ds_read_b128 v[212:215], v147 offset:64
	ds_read_b128 v[216:219], v147 offset:4672
	v_mfma_f32_16x16x32_bf16 v[80:83], v[80:83], v[0:3], 0
	v_mfma_f32_16x16x32_bf16 v[84:87], v[84:87], v[0:3], 0
	v_mfma_f32_16x16x32_bf16 v[88:91], v[88:91], v[0:3], 0
	v_mfma_f32_16x16x32_bf16 v[92:95], v[92:95], v[0:3], 0
	s_waitcnt lgkmcnt(3)
	v_mfma_f32_16x16x32_bf16 v[100:103], v[100:103], v[0:3], 0
	s_waitcnt lgkmcnt(2)
	v_mfma_f32_16x16x32_bf16 v[72:75], v[168:171], v[0:3], 0
	ds_read_b128 v[168:171], v118 offset:51264
	ds_read_b128 v[220:223], v118 offset:55872
	ds_read_b128 v[224:227], v118 offset:60480
	ds_read_b128 v[228:231], v118 offset:65088
	ds_read_b128 v[232:235], v147 offset:9280
	ds_read_b128 v[236:239], v147 offset:13888
	s_waitcnt lgkmcnt(7)
	v_mfma_f32_16x16x32_bf16 v[76:79], v[212:215], v[8:11], v[76:79]
	s_waitcnt lgkmcnt(6)
	v_mfma_f32_16x16x32_bf16 v[96:99], v[216:219], v[8:11], v[96:99]
	ds_read_b128 v[216:219], v147 offset:128
	ds_read_b128 v[240:243], v147 offset:4736
	s_waitcnt lgkmcnt(7)
	v_mfma_f32_16x16x32_bf16 v[80:83], v[168:171], v[8:11], v[80:83]
	s_waitcnt lgkmcnt(6)
	v_mfma_f32_16x16x32_bf16 v[84:87], v[220:223], v[8:11], v[84:87]
	s_waitcnt lgkmcnt(5)
	v_mfma_f32_16x16x32_bf16 v[88:91], v[224:227], v[8:11], v[88:91]
	s_waitcnt lgkmcnt(4)
	v_mfma_f32_16x16x32_bf16 v[92:95], v[228:231], v[8:11], v[92:95]
	s_waitcnt lgkmcnt(3)
	v_mfma_f32_16x16x32_bf16 v[100:103], v[232:235], v[8:11], v[100:103]
	s_waitcnt lgkmcnt(2)
	v_mfma_f32_16x16x32_bf16 v[72:75], v[236:239], v[8:11], v[72:75]
	ds_read_b128 v[168:171], v118 offset:51328
	ds_read_b128 v[188:191], v118 offset:55936
	ds_read_b128 v[220:223], v118 offset:60544
	ds_read_b128 v[224:227], v118 offset:65152
	ds_read_b128 v[228:231], v147 offset:9344
	ds_read_b128 v[232:235], v147 offset:13952
	s_waitcnt lgkmcnt(7)
	v_mfma_f32_16x16x32_bf16 v[76:79], v[216:219], v[16:19], v[76:79]
	s_waitcnt lgkmcnt(6)
	v_mfma_f32_16x16x32_bf16 v[172:175], v[240:243], v[16:19], v[96:99]
	s_nop 2
	ds_read_b128 v[236:239], v147 offset:192
	ds_read_b128 v[240:243], v147 offset:4800
	s_waitcnt lgkmcnt(7)
	v_mfma_f32_16x16x32_bf16 v[168:171], v[168:171], v[16:19], v[80:83]
	s_waitcnt lgkmcnt(6)
	v_mfma_f32_16x16x32_bf16 v[84:87], v[188:191], v[16:19], v[84:87]
	s_waitcnt lgkmcnt(5)
	v_mfma_f32_16x16x32_bf16 v[188:191], v[220:223], v[16:19], v[88:91]
	s_waitcnt lgkmcnt(4)
	v_mfma_f32_16x16x32_bf16 v[220:223], v[224:227], v[16:19], v[92:95]
	s_waitcnt lgkmcnt(3)
	v_mfma_f32_16x16x32_bf16 v[224:227], v[228:231], v[16:19], v[100:103]
	s_waitcnt lgkmcnt(2)
	v_mfma_f32_16x16x32_bf16 v[212:215], v[232:235], v[16:19], v[72:75]
	s_nop 2
	ds_read_b128 v[72:75], v118 offset:51392
	ds_read_b128 v[228:231], v118 offset:56000
	ds_read_b128 v[232:235], v118 offset:60608
	ds_read_b128 v[244:247], v118 offset:65216
	ds_read_b128 v[248:251], v147 offset:9408
	ds_read_b128 v[192:195], v147 offset:14016
	s_waitcnt lgkmcnt(7)
	v_mfma_f32_16x16x32_bf16 v[68:71], v[236:239], v[24:27], v[76:79]
	s_waitcnt lgkmcnt(6)
	v_mfma_f32_16x16x32_bf16 v[64:67], v[240:243], v[24:27], v[172:175]
	s_waitcnt lgkmcnt(5)
	v_mfma_f32_16x16x32_bf16 v[92:95], v[72:75], v[24:27], v[168:171]
	s_waitcnt lgkmcnt(4)
	v_mfma_f32_16x16x32_bf16 v[84:87], v[228:231], v[24:27], v[84:87]
	s_waitcnt lgkmcnt(3)
	v_mfma_f32_16x16x32_bf16 v[76:79], v[232:235], v[24:27], v[188:191]
	s_waitcnt lgkmcnt(2)
	v_mfma_f32_16x16x32_bf16 v[72:75], v[244:247], v[24:27], v[220:223]
	s_waitcnt lgkmcnt(1)
	v_mfma_f32_16x16x32_bf16 v[60:63], v[248:251], v[24:27], v[224:227]
	s_waitcnt lgkmcnt(0)
	v_mfma_f32_16x16x32_bf16 v[56:59], v[192:195], v[24:27], v[212:215]
	s_branch .Lssd_A_join
; #define MFMA16(a, b, c) __builtin_amdgcn_mfma_f32_16x16x32_bf16((a), (b), (c), 0, 0, 0)
; __device__ __forceinline__ void phase_C1(const Args& a, unsigned char* ws, const int bid, int l, LAS unsigned char* lds, int tid, int wave, int lane) {
;     ...
;             {
;                 bf16x8 cqv[2], bq[2][4], hq[2][2];
;     ...
;                 SSD_LDH(0, 0);
; #pragma unroll
;                 for (int h2 = 0; h2 < 8; ++h2) { const int cb = h2 & 1, s_ = h2 >> 1, hf_ = h2 & 1;
;                     if (h2 < 7) SSD_LDH(cb ^ 1, h2 + 1);
;                     __builtin_amdgcn_sched_barrier(0);
; #pragma unroll
;                     for (int k = 0; k < 4; ++k) accA[4 * hf_ + k] = MFMA16(bq[cb][k], cqv[s_ & 1], accA[4 * hf_ + k]);
; #pragma unroll
;                     for (int p = 0; p < 2; ++p) accC[2 * hf_ + p] = MFMA16(hq[cb][p], cqv[s_ & 1], accC[2 * hf_ + p]);
;                     __builtin_amdgcn_sched_barrier(0); }
.Lssd_A_0001:
	ds_read_b128 v[76:79], v147
	ds_read_b128 v[88:91], v118 offset:60416
	ds_read_b128 v[92:95], v118 offset:65024
	ds_read_b128 v[96:99], v147 offset:4608
	ds_read_b128 v[100:103], v147 offset:9216
	ds_read_b128 v[168:171], v147 offset:13824
	s_waitcnt lgkmcnt(5)
	v_mfma_f32_16x16x32_bf16 v[76:79], v[76:79], v[0:3], 0
	s_waitcnt lgkmcnt(2)
	v_mfma_f32_16x16x32_bf16 v[96:99], v[96:99], v[0:3], 0
	ds_read_b128 v[212:215], v147 offset:64
	ds_read_b128 v[216:219], v147 offset:4672
	v_mfma_f32_16x16x32_bf16 v[88:91], v[88:91], v[0:3], 0
	v_mfma_f32_16x16x32_bf16 v[92:95], v[92:95], v[0:3], 0
	s_waitcnt lgkmcnt(3)
	v_mfma_f32_16x16x32_bf16 v[100:103], v[100:103], v[0:3], 0
	s_waitcnt lgkmcnt(2)
	v_mfma_f32_16x16x32_bf16 v[72:75], v[168:171], v[0:3], 0
	ds_read_b128 v[224:227], v118 offset:60480
	ds_read_b128 v[228:231], v118 offset:65088
	ds_read_b128 v[232:235], v147 offset:9280
	ds_read_b128 v[236:239], v147 offset:13888
	s_waitcnt lgkmcnt(5)
	v_mfma_f32_16x16x32_bf16 v[76:79], v[212:215], v[8:11], v[76:79]
	s_waitcnt lgkmcnt(4)
	v_mfma_f32_16x16x32_bf16 v[96:99], v[216:219], v[8:11], v[96:99]
	ds_read_b128 v[216:219], v147 offset:128
	ds_read_b128 v[240:243], v147 offset:4736
	s_waitcnt lgkmcnt(5)
	v_mfma_f32_16x16x32_bf16 v[88:91], v[224:227], v[8:11], v[88:91]
	s_waitcnt lgkmcnt(4)
	v_mfma_f32_16x16x32_bf16 v[92:95], v[228:231], v[8:11], v[92:95]
	s_waitcnt lgkmcnt(3)
	v_mfma_f32_16x16x32_bf16 v[100:103], v[232:235], v[8:11], v[100:103]
	s_waitcnt lgkmcnt(2)
	v_mfma_f32_16x16x32_bf16 v[72:75], v[236:239], v[8:11], v[72:75]
	ds_read_b128 v[220:223], v118 offset:60544
	ds_read_b128 v[224:227], v118 offset:65152
	ds_read_b128 v[228:231], v147 offset:9344
	ds_read_b128 v[232:235], v147 offset:13952
	s_waitcnt lgkmcnt(5)
	v_mfma_f32_16x16x32_bf16 v[76:79], v[216:219], v[16:19], v[76:79]
	s_waitcnt lgkmcnt(4)
	v_mfma_f32_16x16x32_bf16 v[172:175], v[240:243], v[16:19], v[96:99]
	s_nop 2
	ds_read_b128 v[236:239], v147 offset:192
	ds_read_b128 v[240:243], v147 offset:4800
	s_waitcnt lgkmcnt(5)
	v_mfma_f32_16x16x32_bf16 v[188:191], v[220:223], v[16:19], v[88:91]
	s_waitcnt lgkmcnt(4)
	v_mfma_f32_16x16x32_bf16 v[220:223], v[224:227], v[16:19], v[92:95]
	s_waitcnt lgkmcnt(3)
	v_mfma_f32_16x16x32_bf16 v[224:227], v[228:231], v[16:19], v[100:103]
	s_waitcnt lgkmcnt(2)
	v_mfma_f32_16x16x32_bf16 v[212:215], v[232:235], v[16:19], v[72:75]
	s_nop 2
	ds_read_b128 v[232:235], v118 offset:60608
	ds_read_b128 v[244:247], v118 offset:65216
	ds_read_b128 v[248:251], v147 offset:9408
	ds_read_b128 v[192:195], v147 offset:14016
	s_waitcnt lgkmcnt(5)
	v_mfma_f32_16x16x32_bf16 v[68:71], v[236:239], v[24:27], v[76:79]
	s_waitcnt lgkmcnt(4)
	v_mfma_f32_16x16x32_bf16 v[64:67], v[240:243], v[24:27], v[172:175]
	s_waitcnt lgkmcnt(3)
	v_mfma_f32_16x16x32_bf16 v[76:79], v[232:235], v[24:27], v[188:191]
	s_waitcnt lgkmcnt(2)
	v_mfma_f32_16x16x32_bf16 v[72:75], v[244:247], v[24:27], v[220:223]
	s_waitcnt lgkmcnt(1)
	v_mfma_f32_16x16x32_bf16 v[60:63], v[248:251], v[24:27], v[224:227]
	s_waitcnt lgkmcnt(0)
	v_mfma_f32_16x16x32_bf16 v[56:59], v[192:195], v[24:27], v[212:215]
	s_branch .Lssd_A_join
